# v6
# speedup vs baseline: 1.0143x; 1.0088x over previous
.LBB0_269:
	s_add_u32 s26, s24, 0xfff80080
	s_addc_u32 s27, s25, -1
	s_add_i32 s70, 0, 0x10000
	v_add_u32_e32 v148, s70, v154
	ds_read_b128 v[150:153], v148
	ds_read_b128 v[158:161], v148 offset:1024
	ds_read_b128 v[162:165], v148 offset:2048
	ds_read_b128 v[166:169], v148 offset:3072
	s_cmp_eq_u32 s69, 28
	s_cselect_b32 s29, s7, s27
	s_cselect_b32 s28, s6, s26
	s_cselect_b32 s27, s23, s17
	s_cselect_b32 s26, s22, s5
	s_add_i32 m0, s58, 0xc000
	ds_read_b128 v[170:173], v156
	ds_read_b128 v[174:177], v156 offset:1024
	ds_read_b128 v[180:183], v156 offset:2048
	ds_read_b128 v[184:187], v156 offset:3072
	ds_read_b128 v[188:191], v156 offset:4096
	ds_read_b128 v[192:195], v156 offset:5120
	ds_read_b128 v[196:199], v156 offset:6144
	ds_read_b128 v[224:227], v156 offset:7168
	global_load_lds_dwordx4 v146, s[24:25]
	s_add_i32 m0, s58, 0xe000
	s_nop 0
	global_load_lds_dwordx4 v144, s[24:25]
	s_waitcnt lgkmcnt(8)
	s_barrier
	s_waitcnt lgkmcnt(0)
	s_setprio 1
	s_waitcnt lgkmcnt(0)
	v_mfma_f32_16x16x32_bf16 v[124:127], v[150:153], v[170:173], v[124:127]
	v_mfma_f32_16x16x32_bf16 v[120:123], v[162:165], v[170:173], v[120:123]
	v_mfma_f32_16x16x32_bf16 v[108:111], v[150:153], v[180:183], v[108:111]
	v_mfma_f32_16x16x32_bf16 v[104:107], v[162:165], v[180:183], v[104:107]
	v_mfma_f32_16x16x32_bf16 v[92:95], v[150:153], v[188:191], v[92:95]
	v_mfma_f32_16x16x32_bf16 v[88:91], v[162:165], v[188:191], v[88:91]
	v_mfma_f32_16x16x32_bf16 v[76:79], v[150:153], v[196:199], v[76:79]
	v_mfma_f32_16x16x32_bf16 v[72:75], v[162:165], v[196:199], v[72:75]
	v_mfma_f32_16x16x32_bf16 v[124:127], v[158:161], v[174:177], v[124:127]
	v_mfma_f32_16x16x32_bf16 v[120:123], v[166:169], v[174:177], v[120:123]
	v_mfma_f32_16x16x32_bf16 v[108:111], v[158:161], v[184:187], v[108:111]
	v_mfma_f32_16x16x32_bf16 v[104:107], v[166:169], v[184:187], v[104:107]
	v_mfma_f32_16x16x32_bf16 v[92:95], v[158:161], v[192:195], v[92:95]
	v_mfma_f32_16x16x32_bf16 v[88:91], v[166:169], v[192:195], v[88:91]
	v_mfma_f32_16x16x32_bf16 v[76:79], v[158:161], v[224:227], v[76:79]
	v_mfma_f32_16x16x32_bf16 v[72:75], v[166:169], v[224:227], v[72:75]
	s_setprio 0
	s_barrier
	s_add_i32 s72, 0, 0x14000
	s_add_i32 s70, s70, s57
	v_add_u32_e32 v148, s72, v154
	s_mov_b32 m0, s70
	ds_read_b128 v[228:231], v148
	ds_read_b128 v[232:235], v148 offset:1024
	ds_read_b128 v[236:239], v148 offset:2048
	ds_read_b128 v[240:243], v148 offset:3072
	global_load_lds_dwordx4 v130, s[26:27]
	s_add_i32 m0, s70, 0x2000
	s_nop 0
	global_load_lds_dwordx4 v134, s[26:27]
	s_barrier
	s_waitcnt lgkmcnt(0)
	s_setprio 1
	s_waitcnt lgkmcnt(0)
	v_mfma_f32_16x16x32_bf16 v[116:119], v[228:231], v[170:173], v[116:119]
	v_mfma_f32_16x16x32_bf16 v[112:115], v[236:239], v[170:173], v[112:115]
	v_mfma_f32_16x16x32_bf16 v[100:103], v[228:231], v[180:183], v[100:103]
	v_mfma_f32_16x16x32_bf16 v[96:99], v[236:239], v[180:183], v[96:99]
	v_mfma_f32_16x16x32_bf16 v[84:87], v[228:231], v[188:191], v[84:87]
	v_mfma_f32_16x16x32_bf16 v[80:83], v[236:239], v[188:191], v[80:83]
	v_mfma_f32_16x16x32_bf16 v[68:71], v[228:231], v[196:199], v[68:71]
	v_mfma_f32_16x16x32_bf16 v[64:67], v[236:239], v[196:199], v[64:67]
	v_mfma_f32_16x16x32_bf16 v[116:119], v[232:235], v[174:177], v[116:119]
	v_mfma_f32_16x16x32_bf16 v[112:115], v[240:243], v[174:177], v[112:115]
	v_mfma_f32_16x16x32_bf16 v[100:103], v[232:235], v[184:187], v[100:103]
	v_mfma_f32_16x16x32_bf16 v[96:99], v[240:243], v[184:187], v[96:99]
	v_mfma_f32_16x16x32_bf16 v[84:87], v[232:235], v[192:195], v[84:87]
	v_mfma_f32_16x16x32_bf16 v[80:83], v[240:243], v[192:195], v[80:83]
	v_mfma_f32_16x16x32_bf16 v[68:71], v[232:235], v[224:227], v[68:71]
	v_mfma_f32_16x16x32_bf16 v[64:67], v[240:243], v[224:227], v[64:67]
	s_setprio 0
	s_mov_b32 m0, s58
	s_mov_b64 s[100:101], s[28:29]
	s_barrier
	ds_read_b128 v[170:173], v156 offset:16384
	ds_read_b128 v[174:177], v156 offset:17408
	ds_read_b128 v[180:183], v156 offset:18432
	ds_read_b128 v[184:187], v156 offset:19456
	ds_read_b128 v[188:191], v156 offset:20480
	ds_read_b128 v[192:195], v156 offset:21504
	ds_read_b128 v[196:199], v156 offset:22528
	ds_read_b128 v[224:227], v156 offset:23552
	global_load_lds_dwordx4 v128, s[28:29]
	s_mov_b64 s[100:101], s[28:29]
	s_mov_b32 m0, s59
	s_nop 0
	global_load_lds_dwordx4 v132, s[28:29]
	s_barrier
	s_waitcnt lgkmcnt(0)
	s_setprio 1
	s_waitcnt lgkmcnt(0)
	v_mfma_f32_16x16x32_bf16 v[60:63], v[150:153], v[170:173], v[60:63]
	v_mfma_f32_16x16x32_bf16 v[56:59], v[162:165], v[170:173], v[56:59]
	v_mfma_f32_16x16x32_bf16 v[44:47], v[150:153], v[180:183], v[44:47]
	v_mfma_f32_16x16x32_bf16 v[40:43], v[162:165], v[180:183], v[40:43]
	v_mfma_f32_16x16x32_bf16 v[28:31], v[150:153], v[188:191], v[28:31]
	v_mfma_f32_16x16x32_bf16 v[24:27], v[162:165], v[188:191], v[24:27]
	v_mfma_f32_16x16x32_bf16 v[12:15], v[150:153], v[196:199], v[12:15]
	v_mfma_f32_16x16x32_bf16 v[8:11], v[162:165], v[196:199], v[8:11]
	v_mfma_f32_16x16x32_bf16 v[60:63], v[158:161], v[174:177], v[60:63]
	v_mfma_f32_16x16x32_bf16 v[56:59], v[166:169], v[174:177], v[56:59]
	v_mfma_f32_16x16x32_bf16 v[44:47], v[158:161], v[184:187], v[44:47]
	v_mfma_f32_16x16x32_bf16 v[40:43], v[166:169], v[184:187], v[40:43]
	v_mfma_f32_16x16x32_bf16 v[28:31], v[158:161], v[192:195], v[28:31]
	v_mfma_f32_16x16x32_bf16 v[24:27], v[166:169], v[192:195], v[24:27]
	v_mfma_f32_16x16x32_bf16 v[12:15], v[158:161], v[224:227], v[12:15]
	v_mfma_f32_16x16x32_bf16 v[8:11], v[166:169], v[224:227], v[8:11]
	s_setprio 0
	s_barrier
	s_add_u32 s70, s26, 0x80000
	s_addc_u32 s71, s27, 0
	s_add_i32 s72, s72, s57
	s_mov_b32 m0, s72
	s_nop 0
	global_load_lds_dwordx4 v130, s[70:71]
	s_add_i32 m0, s72, 0x2000
	s_nop 0
	global_load_lds_dwordx4 v134, s[70:71]
	s_waitcnt vmcnt(6)
	s_barrier
	s_setprio 1
	v_mfma_f32_16x16x32_bf16 v[52:55], v[228:231], v[170:173], v[52:55]
	v_mfma_f32_16x16x32_bf16 v[48:51], v[236:239], v[170:173], v[48:51]
	v_mfma_f32_16x16x32_bf16 v[36:39], v[228:231], v[180:183], v[36:39]
	v_mfma_f32_16x16x32_bf16 v[32:35], v[236:239], v[180:183], v[32:35]
	v_mfma_f32_16x16x32_bf16 v[20:23], v[228:231], v[188:191], v[20:23]
	v_mfma_f32_16x16x32_bf16 v[16:19], v[236:239], v[188:191], v[16:19]
	v_mfma_f32_16x16x32_bf16 v[4:7], v[228:231], v[196:199], v[4:7]
	v_mfma_f32_16x16x32_bf16 v[0:3], v[236:239], v[196:199], v[0:3]
	v_mfma_f32_16x16x32_bf16 v[52:55], v[232:235], v[174:177], v[52:55]
	v_mfma_f32_16x16x32_bf16 v[48:51], v[240:243], v[174:177], v[48:51]
	v_mfma_f32_16x16x32_bf16 v[36:39], v[232:235], v[184:187], v[36:39]
	v_mfma_f32_16x16x32_bf16 v[32:35], v[240:243], v[184:187], v[32:35]
	v_mfma_f32_16x16x32_bf16 v[20:23], v[232:235], v[192:195], v[20:23]
	v_mfma_f32_16x16x32_bf16 v[16:19], v[240:243], v[192:195], v[16:19]
	v_mfma_f32_16x16x32_bf16 v[4:7], v[232:235], v[224:227], v[4:7]
	v_mfma_f32_16x16x32_bf16 v[0:3], v[240:243], v[224:227], v[0:3]
	s_setprio 0
	s_add_i32 s70, 0, 0x18000
	v_add_u32_e32 v148, s70, v154
	s_barrier
	ds_read_b128 v[150:153], v148
	ds_read_b128 v[158:161], v148 offset:1024
	ds_read_b128 v[162:165], v148 offset:2048
	ds_read_b128 v[166:169], v148 offset:3072
	s_add_u32 s28, s28, 0x80000
	s_addc_u32 s29, s29, 0
	s_mov_b32 m0, s60
	ds_read_b128 v[170:173], v156 offset:32768
	ds_read_b128 v[174:177], v156 offset:33792
	ds_read_b128 v[180:183], v156 offset:34816
	ds_read_b128 v[184:187], v156 offset:35840
	ds_read_b128 v[188:191], v156 offset:36864
	ds_read_b128 v[192:195], v156 offset:37888
	ds_read_b128 v[196:199], v156 offset:38912
	ds_read_b128 v[224:227], v156 offset:39936
	global_load_lds_dwordx4 v128, s[28:29]
	s_mov_b32 m0, s61
	s_nop 0
	global_load_lds_dwordx4 v132, s[28:29]
	s_waitcnt lgkmcnt(8)
	s_barrier
	s_waitcnt lgkmcnt(0)
	s_setprio 1
	s_waitcnt lgkmcnt(0)
	v_mfma_f32_16x16x32_bf16 v[124:127], v[150:153], v[170:173], v[124:127]
	v_mfma_f32_16x16x32_bf16 v[120:123], v[162:165], v[170:173], v[120:123]
	v_mfma_f32_16x16x32_bf16 v[108:111], v[150:153], v[180:183], v[108:111]
	v_mfma_f32_16x16x32_bf16 v[104:107], v[162:165], v[180:183], v[104:107]
	v_mfma_f32_16x16x32_bf16 v[92:95], v[150:153], v[188:191], v[92:95]
	v_mfma_f32_16x16x32_bf16 v[88:91], v[162:165], v[188:191], v[88:91]
	v_mfma_f32_16x16x32_bf16 v[76:79], v[150:153], v[196:199], v[76:79]
	v_mfma_f32_16x16x32_bf16 v[72:75], v[162:165], v[196:199], v[72:75]
	v_mfma_f32_16x16x32_bf16 v[124:127], v[158:161], v[174:177], v[124:127]
	v_mfma_f32_16x16x32_bf16 v[120:123], v[166:169], v[174:177], v[120:123]
	v_mfma_f32_16x16x32_bf16 v[108:111], v[158:161], v[184:187], v[108:111]
	v_mfma_f32_16x16x32_bf16 v[104:107], v[166:169], v[184:187], v[104:107]
	v_mfma_f32_16x16x32_bf16 v[92:95], v[158:161], v[192:195], v[92:95]
	v_mfma_f32_16x16x32_bf16 v[88:91], v[166:169], v[192:195], v[88:91]
	v_mfma_f32_16x16x32_bf16 v[76:79], v[158:161], v[224:227], v[76:79]
	v_mfma_f32_16x16x32_bf16 v[72:75], v[166:169], v[224:227], v[72:75]
	s_setprio 0
	s_barrier
	s_add_i32 s28, 0, 0x1c000
	s_add_i32 s29, s70, s57
	v_add_u32_e32 v148, s28, v154
	s_add_i32 m0, s29, 0xffffff80
	ds_read_b128 v[228:231], v148
	ds_read_b128 v[232:235], v148 offset:1024
	ds_read_b128 v[236:239], v148 offset:2048
	ds_read_b128 v[240:243], v148 offset:3072
	global_load_lds_dwordx4 v130, s[26:27] offset:128
	s_add_i32 m0, s29, 0x1f80
	s_nop 0
	global_load_lds_dwordx4 v134, s[26:27] offset:128
	s_barrier
	s_waitcnt lgkmcnt(0)
	s_setprio 1
	s_waitcnt lgkmcnt(0)
	v_mfma_f32_16x16x32_bf16 v[116:119], v[228:231], v[170:173], v[116:119]
	v_mfma_f32_16x16x32_bf16 v[112:115], v[236:239], v[170:173], v[112:115]
	v_mfma_f32_16x16x32_bf16 v[100:103], v[228:231], v[180:183], v[100:103]
	v_mfma_f32_16x16x32_bf16 v[96:99], v[236:239], v[180:183], v[96:99]
	v_mfma_f32_16x16x32_bf16 v[84:87], v[228:231], v[188:191], v[84:87]
	v_mfma_f32_16x16x32_bf16 v[80:83], v[236:239], v[188:191], v[80:83]
	v_mfma_f32_16x16x32_bf16 v[68:71], v[228:231], v[196:199], v[68:71]
	v_mfma_f32_16x16x32_bf16 v[64:67], v[236:239], v[196:199], v[64:67]
	v_mfma_f32_16x16x32_bf16 v[116:119], v[232:235], v[174:177], v[116:119]
	v_mfma_f32_16x16x32_bf16 v[112:115], v[240:243], v[174:177], v[112:115]
	v_mfma_f32_16x16x32_bf16 v[100:103], v[232:235], v[184:187], v[100:103]
	v_mfma_f32_16x16x32_bf16 v[96:99], v[240:243], v[184:187], v[96:99]
	v_mfma_f32_16x16x32_bf16 v[84:87], v[232:235], v[192:195], v[84:87]
	v_mfma_f32_16x16x32_bf16 v[80:83], v[240:243], v[192:195], v[80:83]
	v_mfma_f32_16x16x32_bf16 v[68:71], v[232:235], v[224:227], v[68:71]
	v_mfma_f32_16x16x32_bf16 v[64:67], v[240:243], v[224:227], v[64:67]
	s_setprio 0
	s_add_i32 m0, s62, 0xffffff80
	s_barrier
	ds_read_b128 v[170:173], v156 offset:49152
	ds_read_b128 v[174:177], v156 offset:50176
	ds_read_b128 v[180:183], v156 offset:51200
	ds_read_b128 v[184:187], v156 offset:52224
	ds_read_b128 v[188:191], v156 offset:53248
	ds_read_b128 v[192:195], v156 offset:54272
	ds_read_b128 v[196:199], v156 offset:55296
	ds_read_b128 v[224:227], v156 offset:56320
	global_load_lds_dwordx4 v128, s[100:101] offset:128
	s_add_i32 m0, s63, 0xffffff80
	s_nop 0
	global_load_lds_dwordx4 v132, s[100:101] offset:128
	s_barrier
	s_waitcnt lgkmcnt(0)
	s_setprio 1
	s_waitcnt lgkmcnt(0)
	v_mfma_f32_16x16x32_bf16 v[60:63], v[150:153], v[170:173], v[60:63]
	v_mfma_f32_16x16x32_bf16 v[56:59], v[162:165], v[170:173], v[56:59]
	v_mfma_f32_16x16x32_bf16 v[44:47], v[150:153], v[180:183], v[44:47]
	v_mfma_f32_16x16x32_bf16 v[40:43], v[162:165], v[180:183], v[40:43]
	v_mfma_f32_16x16x32_bf16 v[28:31], v[150:153], v[188:191], v[28:31]
	v_mfma_f32_16x16x32_bf16 v[24:27], v[162:165], v[188:191], v[24:27]
	v_mfma_f32_16x16x32_bf16 v[12:15], v[150:153], v[196:199], v[12:15]
	v_mfma_f32_16x16x32_bf16 v[8:11], v[162:165], v[196:199], v[8:11]
	v_mfma_f32_16x16x32_bf16 v[60:63], v[158:161], v[174:177], v[60:63]
	v_mfma_f32_16x16x32_bf16 v[56:59], v[166:169], v[174:177], v[56:59]
	v_mfma_f32_16x16x32_bf16 v[44:47], v[158:161], v[184:187], v[44:47]
	v_mfma_f32_16x16x32_bf16 v[40:43], v[166:169], v[184:187], v[40:43]
	v_mfma_f32_16x16x32_bf16 v[28:31], v[158:161], v[192:195], v[28:31]
	v_mfma_f32_16x16x32_bf16 v[24:27], v[166:169], v[192:195], v[24:27]
	v_mfma_f32_16x16x32_bf16 v[12:15], v[158:161], v[224:227], v[12:15]
	v_mfma_f32_16x16x32_bf16 v[8:11], v[166:169], v[224:227], v[8:11]
	s_setprio 0
	s_barrier
	s_add_u32 s26, s26, 0x80080
	s_addc_u32 s27, s27, 0
	s_add_i32 s28, s28, s57
	s_mov_b32 m0, s28
	s_nop 0
	global_load_lds_dwordx4 v130, s[26:27]
	s_add_i32 m0, s28, 0x2000
	s_nop 0
	global_load_lds_dwordx4 v134, s[26:27]
	s_waitcnt vmcnt(6)
	s_barrier
	s_setprio 1
	v_mfma_f32_16x16x32_bf16 v[52:55], v[228:231], v[170:173], v[52:55]
	v_mfma_f32_16x16x32_bf16 v[48:51], v[236:239], v[170:173], v[48:51]
	v_mfma_f32_16x16x32_bf16 v[36:39], v[228:231], v[180:183], v[36:39]
	v_mfma_f32_16x16x32_bf16 v[32:35], v[236:239], v[180:183], v[32:35]
	v_mfma_f32_16x16x32_bf16 v[20:23], v[228:231], v[188:191], v[20:23]
	v_mfma_f32_16x16x32_bf16 v[16:19], v[236:239], v[188:191], v[16:19]
	v_mfma_f32_16x16x32_bf16 v[4:7], v[228:231], v[196:199], v[4:7]
	v_mfma_f32_16x16x32_bf16 v[0:3], v[236:239], v[196:199], v[0:3]
	v_mfma_f32_16x16x32_bf16 v[52:55], v[232:235], v[174:177], v[52:55]
	v_mfma_f32_16x16x32_bf16 v[48:51], v[240:243], v[174:177], v[48:51]
	v_mfma_f32_16x16x32_bf16 v[36:39], v[232:235], v[184:187], v[36:39]
	v_mfma_f32_16x16x32_bf16 v[32:35], v[240:243], v[184:187], v[32:35]
	v_mfma_f32_16x16x32_bf16 v[20:23], v[232:235], v[192:195], v[20:23]
	v_mfma_f32_16x16x32_bf16 v[16:19], v[240:243], v[192:195], v[16:19]
	v_mfma_f32_16x16x32_bf16 v[4:7], v[232:235], v[224:227], v[4:7]
	v_mfma_f32_16x16x32_bf16 v[0:3], v[240:243], v[224:227], v[0:3]
	s_setprio 0
	s_add_i32 s69, s69, 2
	s_add_u32 s5, s5, 0x100
	s_addc_u32 s17, s17, 0
	s_add_u32 s24, s24, 0x100
	s_addc_u32 s25, s25, 0
	s_cmp_gt_u32 s69, 29
	s_barrier
	s_cbranch_scc0 .LBB0_269
	s_lshl_b32 s5, s68, 8
	v_lshl_add_u32 v158, s4, 8, v137
	v_or_b32_e32 v148, s5, v136
	s_addk_i32 s5, 0xf000
	s_lshr_b32 s4, s5, 2
	v_and_b32_e32 v159, 0xffffff80, v158
	s_and_b32 s22, s4, 0x3ffffe00
	v_add_u32_e32 v160, v159, v155
	v_add_u32_e32 v150, s22, v160
	s_lshl_b32 s17, s68, 9
	v_ashrrev_i32_e32 v151, 31, v150
	v_lshlrev_b64 v[152:153], 13, v[150:151]
	v_add_u32_e32 v150, s17, v160
	v_ashrrev_i32_e32 v151, 31, v150
	v_cmp_ne_u32_e64 s[6:7], 0, v149
	s_movk_i32 s4, 0xfff
	v_lshlrev_b64 v[150:151], 10, v[150:151]
	s_and_b64 vcc, exec, s[6:7]
	v_cmp_lt_i32_e64 s[4:5], s4, v148
	v_cvt_pk_bf16_f32 v124, v124, v125
	v_cvt_pk_bf16_f32 v125, v126, v127
	v_cvt_pk_bf16_f32 v126, v120, v121
	v_cvt_pk_bf16_f32 v127, v122, v123
	s_cbranch_vccz .LBB0_290
	s_and_saveexec_b64 s[24:25], s[4:5]
	s_xor_b64 s[4:5], exec, s[24:25]
	v_and_b32_e32 v122, 0x778, v148
	v_lshl_add_u64 v[120:121], v[138:139], 0, v[152:153]
	v_lshlrev_b32_e32 v178, 1, v122
	v_lshl_add_u64 v[122:123], v[120:121], 0, v[178:179]
	s_andn2_saveexec_b64 s[4:5], s[4:5]
	v_lshl_add_u64 v[122:123], v[142:143], 0, v[150:151]
	s_or_b64 exec, exec, s[4:5]
	s_movk_i32 s4, 0x1a00
	v_mad_i64_i32 v[120:121], s[4:5], v158, s4, 0
	s_cbranch_execnz .LBB0_277

.LBB0_935:
	s_add_u32 s12, s10, 0xf4c00080
	s_addc_u32 s13, s11, -1
	s_cmp_lg_u32 s28, 60
	s_cselect_b32 s12, s12, 0
	s_cselect_b32 s13, s13, 0
	s_add_u32 s14, s6, s12
	s_addc_u32 s15, s7, s13
	s_add_i32 s29, 0, 0x10000
	v_add_u32_e32 v150, s29, v140
	ds_read_b128 v[142:145], v150
	ds_read_b128 v[146:149], v150 offset:1024
	ds_read_b128 v[154:157], v150 offset:2048
	ds_read_b128 v[158:161], v150 offset:3072
	s_add_u32 s12, s8, s12
	s_addc_u32 s13, s9, s13
	v_lshl_add_u64 v[150:151], v[136:137], 0, s[10:11]
	s_add_i32 m0, s22, 0xc000
	ds_read_b128 v[162:165], v141
	ds_read_b128 v[166:169], v141 offset:1024
	ds_read_b128 v[170:173], v141 offset:2048
	ds_read_b128 v[174:177], v141 offset:3072
	ds_read_b128 v[180:183], v141 offset:4096
	ds_read_b128 v[184:187], v141 offset:5120
	ds_read_b128 v[188:191], v141 offset:6144
	ds_read_b128 v[192:195], v141 offset:7168
	global_load_lds_dwordx4 v[150:151], off
	v_lshl_add_u64 v[150:151], v[134:135], 0, s[10:11]
	s_add_i32 m0, s22, 0xe000
	s_nop 0
	global_load_lds_dwordx4 v[150:151], off
	s_waitcnt lgkmcnt(8)
	s_barrier
	s_waitcnt lgkmcnt(0)
	s_setprio 1
	s_waitcnt lgkmcnt(0)
	v_mfma_f32_16x16x32_bf16 v[124:127], v[142:145], v[162:165], v[124:127]
	v_mfma_f32_16x16x32_bf16 v[120:123], v[154:157], v[162:165], v[120:123]
	v_mfma_f32_16x16x32_bf16 v[116:119], v[142:145], v[170:173], v[116:119]
	v_mfma_f32_16x16x32_bf16 v[108:111], v[154:157], v[170:173], v[108:111]
	v_mfma_f32_16x16x32_bf16 v[100:103], v[142:145], v[180:183], v[100:103]
	v_mfma_f32_16x16x32_bf16 v[92:95], v[154:157], v[180:183], v[92:95]
	v_mfma_f32_16x16x32_bf16 v[84:87], v[142:145], v[188:191], v[84:87]
	v_mfma_f32_16x16x32_bf16 v[76:79], v[154:157], v[188:191], v[76:79]
	v_mfma_f32_16x16x32_bf16 v[124:127], v[146:149], v[166:169], v[124:127]
	v_mfma_f32_16x16x32_bf16 v[120:123], v[158:161], v[166:169], v[120:123]
	v_mfma_f32_16x16x32_bf16 v[116:119], v[146:149], v[174:177], v[116:119]
	v_mfma_f32_16x16x32_bf16 v[108:111], v[158:161], v[174:177], v[108:111]
	v_mfma_f32_16x16x32_bf16 v[100:103], v[146:149], v[184:187], v[100:103]
	v_mfma_f32_16x16x32_bf16 v[92:95], v[158:161], v[184:187], v[92:95]
	v_mfma_f32_16x16x32_bf16 v[84:87], v[146:149], v[192:195], v[84:87]
	v_mfma_f32_16x16x32_bf16 v[76:79], v[158:161], v[192:195], v[76:79]
	s_setprio 0
	s_barrier
	s_add_i32 s35, 0, 0x14000
	v_add_u32_e32 v150, s35, v140
	s_add_i32 s29, s29, s16
	ds_read_b128 v[196:199], v150
	ds_read_b128 v[224:227], v150 offset:1024
	ds_read_b128 v[228:231], v150 offset:2048
	ds_read_b128 v[232:235], v150 offset:3072
	s_mov_b32 m0, s29
	global_load_lds_dwordx4 v178, s[12:13]
	s_add_i32 m0, s29, 0x2000
	s_nop 0
	global_load_lds_dwordx4 v128, s[12:13]
	s_barrier
	s_waitcnt lgkmcnt(0)
	s_setprio 1
	s_waitcnt lgkmcnt(0)
	v_mfma_f32_16x16x32_bf16 v[112:115], v[196:199], v[162:165], v[112:115]
	v_mfma_f32_16x16x32_bf16 v[104:107], v[228:231], v[162:165], v[104:107]
	v_mfma_f32_16x16x32_bf16 v[96:99], v[196:199], v[170:173], v[96:99]
	v_mfma_f32_16x16x32_bf16 v[88:91], v[228:231], v[170:173], v[88:91]
	v_mfma_f32_16x16x32_bf16 v[80:83], v[196:199], v[180:183], v[80:83]
	v_mfma_f32_16x16x32_bf16 v[72:75], v[228:231], v[180:183], v[72:75]
	v_mfma_f32_16x16x32_bf16 v[68:71], v[196:199], v[188:191], v[68:71]
	v_mfma_f32_16x16x32_bf16 v[64:67], v[228:231], v[188:191], v[64:67]
	v_mfma_f32_16x16x32_bf16 v[112:115], v[224:227], v[166:169], v[112:115]
	v_mfma_f32_16x16x32_bf16 v[104:107], v[232:235], v[166:169], v[104:107]
	v_mfma_f32_16x16x32_bf16 v[96:99], v[224:227], v[174:177], v[96:99]
	v_mfma_f32_16x16x32_bf16 v[88:91], v[232:235], v[174:177], v[88:91]
	v_mfma_f32_16x16x32_bf16 v[80:83], v[224:227], v[184:187], v[80:83]
	v_mfma_f32_16x16x32_bf16 v[72:75], v[232:235], v[184:187], v[72:75]
	v_mfma_f32_16x16x32_bf16 v[68:71], v[224:227], v[192:195], v[68:71]
	v_mfma_f32_16x16x32_bf16 v[64:67], v[232:235], v[192:195], v[64:67]
	s_setprio 0
	s_mov_b32 m0, s22
	s_mov_b64 s[100:101], s[14:15]
	s_barrier
	ds_read_b128 v[162:165], v141 offset:16384
	ds_read_b128 v[166:169], v141 offset:17408
	ds_read_b128 v[170:173], v141 offset:18432
	ds_read_b128 v[174:177], v141 offset:19456
	ds_read_b128 v[180:183], v141 offset:20480
	ds_read_b128 v[184:187], v141 offset:21504
	ds_read_b128 v[188:191], v141 offset:22528
	ds_read_b128 v[192:195], v141 offset:23552
	global_load_lds_dwordx4 v132, s[14:15]
	s_mov_b64 s[100:101], s[14:15]
	s_mov_b32 m0, s23
	s_nop 0
	global_load_lds_dwordx4 v130, s[14:15]
	s_barrier
	s_waitcnt lgkmcnt(0)
	s_setprio 1
	s_waitcnt lgkmcnt(0)
	v_mfma_f32_16x16x32_bf16 v[60:63], v[142:145], v[162:165], v[60:63]
	v_mfma_f32_16x16x32_bf16 v[56:59], v[154:157], v[162:165], v[56:59]
	v_mfma_f32_16x16x32_bf16 v[52:55], v[142:145], v[170:173], v[52:55]
	v_mfma_f32_16x16x32_bf16 v[44:47], v[154:157], v[170:173], v[44:47]
	v_mfma_f32_16x16x32_bf16 v[36:39], v[142:145], v[180:183], v[36:39]
	v_mfma_f32_16x16x32_bf16 v[28:31], v[154:157], v[180:183], v[28:31]
	v_mfma_f32_16x16x32_bf16 v[20:23], v[142:145], v[188:191], v[20:23]
	v_mfma_f32_16x16x32_bf16 v[12:15], v[154:157], v[188:191], v[12:15]
	v_mfma_f32_16x16x32_bf16 v[60:63], v[146:149], v[166:169], v[60:63]
	v_mfma_f32_16x16x32_bf16 v[56:59], v[158:161], v[166:169], v[56:59]
	v_mfma_f32_16x16x32_bf16 v[52:55], v[146:149], v[174:177], v[52:55]
	v_mfma_f32_16x16x32_bf16 v[44:47], v[158:161], v[174:177], v[44:47]
	v_mfma_f32_16x16x32_bf16 v[36:39], v[146:149], v[184:187], v[36:39]
	v_mfma_f32_16x16x32_bf16 v[28:31], v[158:161], v[184:187], v[28:31]
	v_mfma_f32_16x16x32_bf16 v[20:23], v[146:149], v[192:195], v[20:23]
	v_mfma_f32_16x16x32_bf16 v[12:15], v[158:161], v[192:195], v[12:15]
	s_setprio 0
	s_barrier
	s_add_u32 s30, s12, 0x100000
	s_addc_u32 s31, s13, 0
	s_add_i32 s29, s35, s16
	s_mov_b32 m0, s29
	s_nop 0
	global_load_lds_dwordx4 v178, s[30:31]
	s_add_i32 m0, s29, 0x2000
	s_nop 0
	global_load_lds_dwordx4 v128, s[30:31]
	s_waitcnt vmcnt(6)
	s_barrier
	s_setprio 1
	v_mfma_f32_16x16x32_bf16 v[48:51], v[196:199], v[162:165], v[48:51]
	v_mfma_f32_16x16x32_bf16 v[40:43], v[228:231], v[162:165], v[40:43]
	v_mfma_f32_16x16x32_bf16 v[32:35], v[196:199], v[170:173], v[32:35]
	v_mfma_f32_16x16x32_bf16 v[24:27], v[228:231], v[170:173], v[24:27]
	v_mfma_f32_16x16x32_bf16 v[16:19], v[196:199], v[180:183], v[16:19]
	v_mfma_f32_16x16x32_bf16 v[8:11], v[228:231], v[180:183], v[8:11]
	v_mfma_f32_16x16x32_bf16 v[4:7], v[196:199], v[188:191], v[4:7]
	v_mfma_f32_16x16x32_bf16 v[0:3], v[228:231], v[188:191], v[0:3]
	v_mfma_f32_16x16x32_bf16 v[48:51], v[224:227], v[166:169], v[48:51]
	v_mfma_f32_16x16x32_bf16 v[40:43], v[232:235], v[166:169], v[40:43]
	v_mfma_f32_16x16x32_bf16 v[32:35], v[224:227], v[174:177], v[32:35]
	v_mfma_f32_16x16x32_bf16 v[24:27], v[232:235], v[174:177], v[24:27]
	v_mfma_f32_16x16x32_bf16 v[16:19], v[224:227], v[184:187], v[16:19]
	v_mfma_f32_16x16x32_bf16 v[8:11], v[232:235], v[184:187], v[8:11]
	v_mfma_f32_16x16x32_bf16 v[4:7], v[224:227], v[192:195], v[4:7]
	v_mfma_f32_16x16x32_bf16 v[0:3], v[232:235], v[192:195], v[0:3]
	s_setprio 0
	s_add_i32 s29, 0, 0x18000
	v_add_u32_e32 v153, s29, v140
	s_barrier
	ds_read_b128 v[142:145], v153
	ds_read_b128 v[146:149], v153 offset:1024
	ds_read_b128 v[154:157], v153 offset:2048
	ds_read_b128 v[158:161], v153 offset:3072
	s_add_u32 s14, s14, 0x100000
	s_addc_u32 s15, s15, 0
	s_mov_b32 m0, s24
	ds_read_b128 v[162:165], v141 offset:32768
	ds_read_b128 v[166:169], v141 offset:33792
	ds_read_b128 v[170:173], v141 offset:34816
	ds_read_b128 v[174:177], v141 offset:35840
	ds_read_b128 v[180:183], v141 offset:36864
	ds_read_b128 v[184:187], v141 offset:37888
	ds_read_b128 v[188:191], v141 offset:38912
	ds_read_b128 v[192:195], v141 offset:39936
	global_load_lds_dwordx4 v132, s[14:15]
	s_mov_b32 m0, s25
	s_nop 0
	global_load_lds_dwordx4 v130, s[14:15]
	s_waitcnt lgkmcnt(8)
	s_barrier
	s_waitcnt lgkmcnt(0)
	s_setprio 1
	s_waitcnt lgkmcnt(0)
	v_mfma_f32_16x16x32_bf16 v[124:127], v[142:145], v[162:165], v[124:127]
	v_mfma_f32_16x16x32_bf16 v[120:123], v[154:157], v[162:165], v[120:123]
	v_mfma_f32_16x16x32_bf16 v[116:119], v[142:145], v[170:173], v[116:119]
	v_mfma_f32_16x16x32_bf16 v[108:111], v[154:157], v[170:173], v[108:111]
	v_mfma_f32_16x16x32_bf16 v[100:103], v[142:145], v[180:183], v[100:103]
	v_mfma_f32_16x16x32_bf16 v[92:95], v[154:157], v[180:183], v[92:95]
	v_mfma_f32_16x16x32_bf16 v[84:87], v[142:145], v[188:191], v[84:87]
	v_mfma_f32_16x16x32_bf16 v[76:79], v[154:157], v[188:191], v[76:79]
	v_mfma_f32_16x16x32_bf16 v[124:127], v[146:149], v[166:169], v[124:127]
	v_mfma_f32_16x16x32_bf16 v[120:123], v[158:161], v[166:169], v[120:123]
	v_mfma_f32_16x16x32_bf16 v[116:119], v[146:149], v[174:177], v[116:119]
	v_mfma_f32_16x16x32_bf16 v[108:111], v[158:161], v[174:177], v[108:111]
	v_mfma_f32_16x16x32_bf16 v[100:103], v[146:149], v[184:187], v[100:103]
	v_mfma_f32_16x16x32_bf16 v[92:95], v[158:161], v[184:187], v[92:95]
	v_mfma_f32_16x16x32_bf16 v[84:87], v[146:149], v[192:195], v[84:87]
	v_mfma_f32_16x16x32_bf16 v[76:79], v[158:161], v[192:195], v[76:79]
	s_setprio 0
	s_barrier
	s_add_i32 s14, 0, 0x1c000
	s_add_i32 s15, s29, s16
	v_add_u32_e32 v153, s14, v140
	s_add_i32 m0, s15, 0xffffff80
	ds_read_b128 v[196:199], v153
	ds_read_b128 v[224:227], v153 offset:1024
	ds_read_b128 v[228:231], v153 offset:2048
	ds_read_b128 v[232:235], v153 offset:3072
	global_load_lds_dwordx4 v178, s[12:13] offset:128
	s_add_i32 m0, s15, 0x1f80
	s_nop 0
	global_load_lds_dwordx4 v128, s[12:13] offset:128
	s_barrier
	s_waitcnt lgkmcnt(0)
	s_setprio 1
	s_waitcnt lgkmcnt(0)
	v_mfma_f32_16x16x32_bf16 v[112:115], v[196:199], v[162:165], v[112:115]
	v_mfma_f32_16x16x32_bf16 v[104:107], v[228:231], v[162:165], v[104:107]
	v_mfma_f32_16x16x32_bf16 v[96:99], v[196:199], v[170:173], v[96:99]
	v_mfma_f32_16x16x32_bf16 v[88:91], v[228:231], v[170:173], v[88:91]
	v_mfma_f32_16x16x32_bf16 v[80:83], v[196:199], v[180:183], v[80:83]
	v_mfma_f32_16x16x32_bf16 v[72:75], v[228:231], v[180:183], v[72:75]
	v_mfma_f32_16x16x32_bf16 v[68:71], v[196:199], v[188:191], v[68:71]
	v_mfma_f32_16x16x32_bf16 v[64:67], v[228:231], v[188:191], v[64:67]
	v_mfma_f32_16x16x32_bf16 v[112:115], v[224:227], v[166:169], v[112:115]
	v_mfma_f32_16x16x32_bf16 v[104:107], v[232:235], v[166:169], v[104:107]
	v_mfma_f32_16x16x32_bf16 v[96:99], v[224:227], v[174:177], v[96:99]
	v_mfma_f32_16x16x32_bf16 v[88:91], v[232:235], v[174:177], v[88:91]
	v_mfma_f32_16x16x32_bf16 v[80:83], v[224:227], v[184:187], v[80:83]
	v_mfma_f32_16x16x32_bf16 v[72:75], v[232:235], v[184:187], v[72:75]
	v_mfma_f32_16x16x32_bf16 v[68:71], v[224:227], v[192:195], v[68:71]
	v_mfma_f32_16x16x32_bf16 v[64:67], v[232:235], v[192:195], v[64:67]
	s_setprio 0
	s_add_i32 m0, s26, 0xffffff80
	s_barrier
	ds_read_b128 v[162:165], v141 offset:49152
	ds_read_b128 v[166:169], v141 offset:50176
	ds_read_b128 v[170:173], v141 offset:51200
	ds_read_b128 v[174:177], v141 offset:52224
	ds_read_b128 v[180:183], v141 offset:53248
	ds_read_b128 v[184:187], v141 offset:54272
	ds_read_b128 v[188:191], v141 offset:55296
	ds_read_b128 v[192:195], v141 offset:56320
	global_load_lds_dwordx4 v132, s[100:101] offset:128
	s_add_i32 m0, s27, 0xffffff80
	s_nop 0
	global_load_lds_dwordx4 v130, s[100:101] offset:128
	s_barrier
	s_waitcnt lgkmcnt(0)
	s_setprio 1
	s_waitcnt lgkmcnt(0)
	v_mfma_f32_16x16x32_bf16 v[60:63], v[142:145], v[162:165], v[60:63]
	v_mfma_f32_16x16x32_bf16 v[56:59], v[154:157], v[162:165], v[56:59]
	v_mfma_f32_16x16x32_bf16 v[52:55], v[142:145], v[170:173], v[52:55]
	v_mfma_f32_16x16x32_bf16 v[44:47], v[154:157], v[170:173], v[44:47]
	v_mfma_f32_16x16x32_bf16 v[36:39], v[142:145], v[180:183], v[36:39]
	v_mfma_f32_16x16x32_bf16 v[28:31], v[154:157], v[180:183], v[28:31]
	v_mfma_f32_16x16x32_bf16 v[20:23], v[142:145], v[188:191], v[20:23]
	v_mfma_f32_16x16x32_bf16 v[12:15], v[154:157], v[188:191], v[12:15]
	v_mfma_f32_16x16x32_bf16 v[60:63], v[146:149], v[166:169], v[60:63]
	v_mfma_f32_16x16x32_bf16 v[56:59], v[158:161], v[166:169], v[56:59]
	v_mfma_f32_16x16x32_bf16 v[52:55], v[146:149], v[174:177], v[52:55]
	v_mfma_f32_16x16x32_bf16 v[44:47], v[158:161], v[174:177], v[44:47]
	v_mfma_f32_16x16x32_bf16 v[36:39], v[146:149], v[184:187], v[36:39]
	v_mfma_f32_16x16x32_bf16 v[28:31], v[158:161], v[184:187], v[28:31]
	v_mfma_f32_16x16x32_bf16 v[20:23], v[146:149], v[192:195], v[20:23]
	v_mfma_f32_16x16x32_bf16 v[12:15], v[158:161], v[192:195], v[12:15]
	s_setprio 0
	s_barrier
	s_add_u32 s12, s12, 0x100080
	s_addc_u32 s13, s13, 0
	s_add_i32 s14, s14, s16
	s_mov_b32 m0, s14
	s_nop 0
	global_load_lds_dwordx4 v178, s[12:13]
	s_add_i32 m0, s14, 0x2000
	s_nop 0
	global_load_lds_dwordx4 v128, s[12:13]
	s_waitcnt vmcnt(6)
	s_barrier
	s_setprio 1
	v_mfma_f32_16x16x32_bf16 v[48:51], v[196:199], v[162:165], v[48:51]
	v_mfma_f32_16x16x32_bf16 v[40:43], v[228:231], v[162:165], v[40:43]
	v_mfma_f32_16x16x32_bf16 v[32:35], v[196:199], v[170:173], v[32:35]
	v_mfma_f32_16x16x32_bf16 v[24:27], v[228:231], v[170:173], v[24:27]
	v_mfma_f32_16x16x32_bf16 v[16:19], v[196:199], v[180:183], v[16:19]
	v_mfma_f32_16x16x32_bf16 v[8:11], v[228:231], v[180:183], v[8:11]
	v_mfma_f32_16x16x32_bf16 v[4:7], v[196:199], v[188:191], v[4:7]
	v_mfma_f32_16x16x32_bf16 v[0:3], v[228:231], v[188:191], v[0:3]
	v_mfma_f32_16x16x32_bf16 v[48:51], v[224:227], v[166:169], v[48:51]
	v_mfma_f32_16x16x32_bf16 v[40:43], v[232:235], v[166:169], v[40:43]
	v_mfma_f32_16x16x32_bf16 v[32:35], v[224:227], v[174:177], v[32:35]
	v_mfma_f32_16x16x32_bf16 v[24:27], v[232:235], v[174:177], v[24:27]
	v_mfma_f32_16x16x32_bf16 v[16:19], v[224:227], v[184:187], v[16:19]
	v_mfma_f32_16x16x32_bf16 v[8:11], v[232:235], v[184:187], v[8:11]
	v_mfma_f32_16x16x32_bf16 v[4:7], v[224:227], v[192:195], v[4:7]
	v_mfma_f32_16x16x32_bf16 v[0:3], v[232:235], v[192:195], v[0:3]
	s_setprio 0
	s_add_i32 s28, s28, 2
	s_add_u32 s10, s10, 0x100
	s_addc_u32 s11, s11, 0
	s_cmp_gt_u32 s28, 61
	s_barrier
	s_cbranch_scc0 .LBB0_935
	v_readlane_b32 s6, v253, 51
	s_or_b32 s6, s17, s6
	v_cvt_pk_bf16_f32 v124, v124, v125
	v_cvt_pk_bf16_f32 v125, v126, v127
	v_cvt_pk_bf16_f32 v126, v120, v121
	v_cvt_pk_bf16_f32 v127, v122, v123
	s_nop 0
	v_or_b32_e32 v130, s6, v139
	v_readlane_b32 s6, v253, 44
	v_lshlrev_b32_e32 v178, 1, v130
	s_nop 0
	v_add_u32_e32 v131, s6, v138
	v_add_u32_e32 v128, 0x1000, v131
	v_ashrrev_i32_e32 v129, 31, v128
	v_lshlrev_b64 v[128:129], 12, v[128:129]
	v_lshl_add_u64 v[128:129], s[4:5], 0, v[128:129]
	v_lshl_add_u64 v[128:129], v[128:129], 0, v[178:179]
	global_store_dwordx4 v[128:129], v[124:127], off
	v_cvt_pk_bf16_f32 v112, v112, v113
	v_cvt_pk_bf16_f32 v113, v114, v115
	v_cvt_pk_bf16_f32 v114, v104, v105
	v_add_u32_e32 v104, 0x1010, v131
	v_ashrrev_i32_e32 v105, 31, v104
	v_lshlrev_b64 v[104:105], 12, v[104:105]
	v_lshl_add_u64 v[104:105], s[4:5], 0, v[104:105]
	v_cvt_pk_bf16_f32 v115, v106, v107
	global_store_dwordx4 v[128:129], v[112:115], off offset:256
	v_readlane_b32 s6, v255, 8
	s_nop 0
	v_lshl_add_u64 v[112:113], v[104:105], 0, v[178:179]
	v_cvt_pk_bf16_f32 v104, v116, v117
	v_cvt_pk_bf16_f32 v105, v118, v119
	v_cvt_pk_bf16_f32 v106, v108, v109
	v_cvt_pk_bf16_f32 v107, v110, v111
	global_store_dwordx4 v[112:113], v[104:107], off
	v_cvt_pk_bf16_f32 v96, v96, v97
	v_cvt_pk_bf16_f32 v97, v98, v99
	v_cvt_pk_bf16_f32 v98, v88, v89
	v_add_u32_e32 v88, 0x1020, v131
	v_ashrrev_i32_e32 v89, 31, v88
	v_lshlrev_b64 v[88:89], 12, v[88:89]
	v_lshl_add_u64 v[88:89], s[4:5], 0, v[88:89]
	v_cvt_pk_bf16_f32 v99, v90, v91
	global_store_dwordx4 v[112:113], v[96:99], off offset:256
	s_nop 1
	v_lshl_add_u64 v[96:97], v[88:89], 0, v[178:179]
	v_cvt_pk_bf16_f32 v88, v100, v101
	v_cvt_pk_bf16_f32 v89, v102, v103
	v_cvt_pk_bf16_f32 v90, v92, v93
	v_cvt_pk_bf16_f32 v91, v94, v95
	global_store_dwordx4 v[96:97], v[88:91], off
	v_cvt_pk_bf16_f32 v80, v80, v81
	v_cvt_pk_bf16_f32 v81, v82, v83
	v_cvt_pk_bf16_f32 v82, v72, v73
	v_add_u32_e32 v72, 0x1030, v131
	v_ashrrev_i32_e32 v73, 31, v72
	v_lshlrev_b64 v[72:73], 12, v[72:73]
	v_lshl_add_u64 v[72:73], s[4:5], 0, v[72:73]
	v_cvt_pk_bf16_f32 v83, v74, v75
	global_store_dwordx4 v[96:97], v[80:83], off offset:256
	s_nop 1
	v_lshl_add_u64 v[80:81], v[72:73], 0, v[178:179]
	v_cvt_pk_bf16_f32 v72, v84, v85
	v_cvt_pk_bf16_f32 v73, v86, v87
	v_cvt_pk_bf16_f32 v74, v76, v77
	v_cvt_pk_bf16_f32 v75, v78, v79
	global_store_dwordx4 v[80:81], v[72:75], off
	v_cvt_pk_bf16_f32 v68, v68, v69
	v_cvt_pk_bf16_f32 v69, v70, v71
	v_cvt_pk_bf16_f32 v70, v64, v65
	v_add_u32_e32 v64, 0x1080, v131
	v_ashrrev_i32_e32 v65, 31, v64
	v_lshlrev_b64 v[64:65], 12, v[64:65]
	v_lshl_add_u64 v[64:65], s[4:5], 0, v[64:65]
	v_lshl_add_u64 v[64:65], v[64:65], 0, v[178:179]
	v_cvt_pk_bf16_f32 v71, v66, v67
	global_store_dwordx4 v[80:81], v[68:71], off offset:256
	v_cvt_pk_bf16_f32 v60, v60, v61
	v_cvt_pk_bf16_f32 v61, v62, v63
	v_cvt_pk_bf16_f32 v62, v56, v57
	v_cvt_pk_bf16_f32 v63, v58, v59
	global_store_dwordx4 v[64:65], v[60:63], off
	v_cvt_pk_bf16_f32 v48, v48, v49
	v_cvt_pk_bf16_f32 v49, v50, v51
	v_cvt_pk_bf16_f32 v50, v40, v41
	v_add_u32_e32 v40, 0x1090, v131
	v_ashrrev_i32_e32 v41, 31, v40
	v_lshlrev_b64 v[40:41], 12, v[40:41]
	v_lshl_add_u64 v[40:41], s[4:5], 0, v[40:41]
	v_cvt_pk_bf16_f32 v51, v42, v43
	global_store_dwordx4 v[64:65], v[48:51], off offset:256
	s_nop 1
	v_lshl_add_u64 v[48:49], v[40:41], 0, v[178:179]
	v_cvt_pk_bf16_f32 v40, v52, v53
	v_cvt_pk_bf16_f32 v41, v54, v55
	v_cvt_pk_bf16_f32 v42, v44, v45
	v_cvt_pk_bf16_f32 v43, v46, v47
	global_store_dwordx4 v[48:49], v[40:43], off
	v_cvt_pk_bf16_f32 v32, v32, v33
	v_cvt_pk_bf16_f32 v33, v34, v35
	v_cvt_pk_bf16_f32 v34, v24, v25
	v_add_u32_e32 v24, 0x10a0, v131
	v_ashrrev_i32_e32 v25, 31, v24
	v_lshlrev_b64 v[24:25], 12, v[24:25]
	v_lshl_add_u64 v[24:25], s[4:5], 0, v[24:25]
	v_cvt_pk_bf16_f32 v35, v26, v27
	global_store_dwordx4 v[48:49], v[32:35], off offset:256
	s_nop 1
	v_lshl_add_u64 v[32:33], v[24:25], 0, v[178:179]
	v_cvt_pk_bf16_f32 v24, v36, v37
	v_cvt_pk_bf16_f32 v25, v38, v39
	v_cvt_pk_bf16_f32 v26, v28, v29
	v_cvt_pk_bf16_f32 v27, v30, v31
	global_store_dwordx4 v[32:33], v[24:27], off
	v_cvt_pk_bf16_f32 v16, v16, v17
	v_cvt_pk_bf16_f32 v17, v18, v19
	v_cvt_pk_bf16_f32 v18, v8, v9
	v_add_u32_e32 v8, 0x10b0, v131
	v_ashrrev_i32_e32 v9, 31, v8
	v_lshlrev_b64 v[8:9], 12, v[8:9]
	v_lshl_add_u64 v[8:9], s[4:5], 0, v[8:9]
	v_cvt_pk_bf16_f32 v19, v10, v11
	global_store_dwordx4 v[32:33], v[16:19], off offset:256
	s_nop 1
	v_lshl_add_u64 v[16:17], v[8:9], 0, v[178:179]
	v_cvt_pk_bf16_f32 v8, v20, v21
	v_cvt_pk_bf16_f32 v9, v22, v23
	v_cvt_pk_bf16_f32 v10, v12, v13
	v_cvt_pk_bf16_f32 v11, v14, v15
	global_store_dwordx4 v[16:17], v[8:11], off
	v_cvt_pk_bf16_f32 v4, v4, v5
	v_cvt_pk_bf16_f32 v5, v6, v7
	v_cvt_pk_bf16_f32 v6, v0, v1
	v_cvt_pk_bf16_f32 v7, v2, v3
	global_store_dwordx4 v[16:17], v[4:7], off offset:256
	s_waitcnt vmcnt(0)
	s_cmp_lt_u32 s6, 4
	s_cbranch_scc0 .LBB0_938
	s_barrier

.LBB0_943:
	s_add_u32 s12, s10, 0xf3ce0080
	s_addc_u32 s13, s11, -1
	s_cmp_lg_u32 s20, 4
	s_cselect_b32 s12, s12, 0
	s_cselect_b32 s13, s13, 0
	s_add_u32 s14, s6, s12
	s_addc_u32 s15, s7, s13
	s_add_i32 s21, 0, 0x10000
	v_add_u32_e32 v150, s21, v140
	ds_read_b128 v[142:145], v150
	ds_read_b128 v[146:149], v150 offset:1024
	ds_read_b128 v[154:157], v150 offset:2048
	ds_read_b128 v[158:161], v150 offset:3072
	s_add_u32 s12, s8, s12
	s_addc_u32 s13, s9, s13
	v_lshl_add_u64 v[150:151], v[136:137], 0, s[10:11]
	s_add_i32 m0, s22, 0xc000
	ds_read_b128 v[162:165], v141
	ds_read_b128 v[166:169], v141 offset:1024
	ds_read_b128 v[170:173], v141 offset:2048
	ds_read_b128 v[174:177], v141 offset:3072
	ds_read_b128 v[180:183], v141 offset:4096
	ds_read_b128 v[184:187], v141 offset:5120
	ds_read_b128 v[188:191], v141 offset:6144
	ds_read_b128 v[192:195], v141 offset:7168
	global_load_lds_dwordx4 v[150:151], off
	v_lshl_add_u64 v[150:151], v[134:135], 0, s[10:11]
	s_add_i32 m0, s22, 0xe000
	s_nop 0
	global_load_lds_dwordx4 v[150:151], off
	s_waitcnt lgkmcnt(8)
	s_barrier
	s_waitcnt lgkmcnt(0)
	s_setprio 1
	s_waitcnt lgkmcnt(0)
	v_mfma_f32_16x16x32_bf16 v[124:127], v[142:145], v[162:165], v[124:127]
	v_mfma_f32_16x16x32_bf16 v[120:123], v[154:157], v[162:165], v[120:123]
	v_mfma_f32_16x16x32_bf16 v[116:119], v[142:145], v[170:173], v[116:119]
	v_mfma_f32_16x16x32_bf16 v[108:111], v[154:157], v[170:173], v[108:111]
	v_mfma_f32_16x16x32_bf16 v[100:103], v[142:145], v[180:183], v[100:103]
	v_mfma_f32_16x16x32_bf16 v[92:95], v[154:157], v[180:183], v[92:95]
	v_mfma_f32_16x16x32_bf16 v[84:87], v[142:145], v[188:191], v[84:87]
	v_mfma_f32_16x16x32_bf16 v[76:79], v[154:157], v[188:191], v[76:79]
	v_mfma_f32_16x16x32_bf16 v[124:127], v[146:149], v[166:169], v[124:127]
	v_mfma_f32_16x16x32_bf16 v[120:123], v[158:161], v[166:169], v[120:123]
	v_mfma_f32_16x16x32_bf16 v[116:119], v[146:149], v[174:177], v[116:119]
	v_mfma_f32_16x16x32_bf16 v[108:111], v[158:161], v[174:177], v[108:111]
	v_mfma_f32_16x16x32_bf16 v[100:103], v[146:149], v[184:187], v[100:103]
	v_mfma_f32_16x16x32_bf16 v[92:95], v[158:161], v[184:187], v[92:95]
	v_mfma_f32_16x16x32_bf16 v[84:87], v[146:149], v[192:195], v[84:87]
	v_mfma_f32_16x16x32_bf16 v[76:79], v[158:161], v[192:195], v[76:79]
	s_setprio 0
	s_barrier
	s_add_i32 s28, 0, 0x14000
	v_add_u32_e32 v150, s28, v140
	s_add_i32 s21, s21, s16
	ds_read_b128 v[196:199], v150
	ds_read_b128 v[224:227], v150 offset:1024
	ds_read_b128 v[228:231], v150 offset:2048
	ds_read_b128 v[232:235], v150 offset:3072
	s_mov_b32 m0, s21
	global_load_lds_dwordx4 v178, s[12:13]
	s_add_i32 m0, s21, 0x2000
	s_nop 0
	global_load_lds_dwordx4 v128, s[12:13]
	s_barrier
	s_waitcnt lgkmcnt(0)
	s_setprio 1
	s_waitcnt lgkmcnt(0)
	v_mfma_f32_16x16x32_bf16 v[112:115], v[196:199], v[162:165], v[112:115]
	v_mfma_f32_16x16x32_bf16 v[104:107], v[228:231], v[162:165], v[104:107]
	v_mfma_f32_16x16x32_bf16 v[96:99], v[196:199], v[170:173], v[96:99]
	v_mfma_f32_16x16x32_bf16 v[88:91], v[228:231], v[170:173], v[88:91]
	v_mfma_f32_16x16x32_bf16 v[80:83], v[196:199], v[180:183], v[80:83]
	v_mfma_f32_16x16x32_bf16 v[72:75], v[228:231], v[180:183], v[72:75]
	v_mfma_f32_16x16x32_bf16 v[68:71], v[196:199], v[188:191], v[68:71]
	v_mfma_f32_16x16x32_bf16 v[64:67], v[228:231], v[188:191], v[64:67]
	v_mfma_f32_16x16x32_bf16 v[112:115], v[224:227], v[166:169], v[112:115]
	v_mfma_f32_16x16x32_bf16 v[104:107], v[232:235], v[166:169], v[104:107]
	v_mfma_f32_16x16x32_bf16 v[96:99], v[224:227], v[174:177], v[96:99]
	v_mfma_f32_16x16x32_bf16 v[88:91], v[232:235], v[174:177], v[88:91]
	v_mfma_f32_16x16x32_bf16 v[80:83], v[224:227], v[184:187], v[80:83]
	v_mfma_f32_16x16x32_bf16 v[72:75], v[232:235], v[184:187], v[72:75]
	v_mfma_f32_16x16x32_bf16 v[68:71], v[224:227], v[192:195], v[68:71]
	v_mfma_f32_16x16x32_bf16 v[64:67], v[232:235], v[192:195], v[64:67]
	s_setprio 0
	s_mov_b32 m0, s22
	s_mov_b64 s[100:101], s[14:15]
	s_barrier
	ds_read_b128 v[162:165], v141 offset:16384
	ds_read_b128 v[166:169], v141 offset:17408
	ds_read_b128 v[170:173], v141 offset:18432
	ds_read_b128 v[174:177], v141 offset:19456
	ds_read_b128 v[180:183], v141 offset:20480
	ds_read_b128 v[184:187], v141 offset:21504
	ds_read_b128 v[188:191], v141 offset:22528
	ds_read_b128 v[192:195], v141 offset:23552
	global_load_lds_dwordx4 v132, s[14:15]
	s_mov_b64 s[100:101], s[14:15]
	s_mov_b32 m0, s23
	s_nop 0
	global_load_lds_dwordx4 v130, s[14:15]
	s_barrier
	s_waitcnt lgkmcnt(0)
	s_setprio 1
	s_waitcnt lgkmcnt(0)
	v_mfma_f32_16x16x32_bf16 v[60:63], v[142:145], v[162:165], v[60:63]
	v_mfma_f32_16x16x32_bf16 v[56:59], v[154:157], v[162:165], v[56:59]
	v_mfma_f32_16x16x32_bf16 v[52:55], v[142:145], v[170:173], v[52:55]
	v_mfma_f32_16x16x32_bf16 v[44:47], v[154:157], v[170:173], v[44:47]
	v_mfma_f32_16x16x32_bf16 v[36:39], v[142:145], v[180:183], v[36:39]
	v_mfma_f32_16x16x32_bf16 v[28:31], v[154:157], v[180:183], v[28:31]
	v_mfma_f32_16x16x32_bf16 v[20:23], v[142:145], v[188:191], v[20:23]
	v_mfma_f32_16x16x32_bf16 v[12:15], v[154:157], v[188:191], v[12:15]
	v_mfma_f32_16x16x32_bf16 v[60:63], v[146:149], v[166:169], v[60:63]
	v_mfma_f32_16x16x32_bf16 v[56:59], v[158:161], v[166:169], v[56:59]
	v_mfma_f32_16x16x32_bf16 v[52:55], v[146:149], v[174:177], v[52:55]
	v_mfma_f32_16x16x32_bf16 v[44:47], v[158:161], v[174:177], v[44:47]
	v_mfma_f32_16x16x32_bf16 v[36:39], v[146:149], v[184:187], v[36:39]
	v_mfma_f32_16x16x32_bf16 v[28:31], v[158:161], v[184:187], v[28:31]
	v_mfma_f32_16x16x32_bf16 v[20:23], v[146:149], v[192:195], v[20:23]
	v_mfma_f32_16x16x32_bf16 v[12:15], v[158:161], v[192:195], v[12:15]
	s_setprio 0
	s_barrier
	s_add_u32 s26, s12, 0x20000
	s_addc_u32 s27, s13, 0
	s_add_i32 s21, s28, s16
	s_mov_b32 m0, s21
	s_nop 0
	global_load_lds_dwordx4 v178, s[26:27]
	s_add_i32 m0, s21, 0x2000
	s_nop 0
	global_load_lds_dwordx4 v128, s[26:27]
	s_waitcnt vmcnt(6)
	s_barrier
	s_setprio 1
	v_mfma_f32_16x16x32_bf16 v[48:51], v[196:199], v[162:165], v[48:51]
	v_mfma_f32_16x16x32_bf16 v[40:43], v[228:231], v[162:165], v[40:43]
	v_mfma_f32_16x16x32_bf16 v[32:35], v[196:199], v[170:173], v[32:35]
	v_mfma_f32_16x16x32_bf16 v[24:27], v[228:231], v[170:173], v[24:27]
	v_mfma_f32_16x16x32_bf16 v[16:19], v[196:199], v[180:183], v[16:19]
	v_mfma_f32_16x16x32_bf16 v[8:11], v[228:231], v[180:183], v[8:11]
	v_mfma_f32_16x16x32_bf16 v[4:7], v[196:199], v[188:191], v[4:7]
	v_mfma_f32_16x16x32_bf16 v[0:3], v[228:231], v[188:191], v[0:3]
	v_mfma_f32_16x16x32_bf16 v[48:51], v[224:227], v[166:169], v[48:51]
	v_mfma_f32_16x16x32_bf16 v[40:43], v[232:235], v[166:169], v[40:43]
	v_mfma_f32_16x16x32_bf16 v[32:35], v[224:227], v[174:177], v[32:35]
	v_mfma_f32_16x16x32_bf16 v[24:27], v[232:235], v[174:177], v[24:27]
	v_mfma_f32_16x16x32_bf16 v[16:19], v[224:227], v[184:187], v[16:19]
	v_mfma_f32_16x16x32_bf16 v[8:11], v[232:235], v[184:187], v[8:11]
	v_mfma_f32_16x16x32_bf16 v[4:7], v[224:227], v[192:195], v[4:7]
	v_mfma_f32_16x16x32_bf16 v[0:3], v[232:235], v[192:195], v[0:3]
	s_setprio 0
	s_add_i32 s21, 0, 0x18000
	v_add_u32_e32 v153, s21, v140
	s_barrier
	ds_read_b128 v[142:145], v153
	ds_read_b128 v[146:149], v153 offset:1024
	ds_read_b128 v[154:157], v153 offset:2048
	ds_read_b128 v[158:161], v153 offset:3072
	s_add_u32 s14, s14, 0x20000
	s_addc_u32 s15, s15, 0
	s_mov_b32 m0, s24
	ds_read_b128 v[162:165], v141 offset:32768
	ds_read_b128 v[166:169], v141 offset:33792
	ds_read_b128 v[170:173], v141 offset:34816
	ds_read_b128 v[174:177], v141 offset:35840
	ds_read_b128 v[180:183], v141 offset:36864
	ds_read_b128 v[184:187], v141 offset:37888
	ds_read_b128 v[188:191], v141 offset:38912
	ds_read_b128 v[192:195], v141 offset:39936
	global_load_lds_dwordx4 v132, s[14:15]
	s_mov_b32 m0, s25
	s_nop 0
	global_load_lds_dwordx4 v130, s[14:15]
	s_waitcnt lgkmcnt(8)
	s_barrier
	s_waitcnt lgkmcnt(0)
	s_setprio 1
	s_waitcnt lgkmcnt(0)
	v_mfma_f32_16x16x32_bf16 v[124:127], v[142:145], v[162:165], v[124:127]
	v_mfma_f32_16x16x32_bf16 v[120:123], v[154:157], v[162:165], v[120:123]
	v_mfma_f32_16x16x32_bf16 v[116:119], v[142:145], v[170:173], v[116:119]
	v_mfma_f32_16x16x32_bf16 v[108:111], v[154:157], v[170:173], v[108:111]
	v_mfma_f32_16x16x32_bf16 v[100:103], v[142:145], v[180:183], v[100:103]
	v_mfma_f32_16x16x32_bf16 v[92:95], v[154:157], v[180:183], v[92:95]
	v_mfma_f32_16x16x32_bf16 v[84:87], v[142:145], v[188:191], v[84:87]
	v_mfma_f32_16x16x32_bf16 v[76:79], v[154:157], v[188:191], v[76:79]
	v_mfma_f32_16x16x32_bf16 v[124:127], v[146:149], v[166:169], v[124:127]
	v_mfma_f32_16x16x32_bf16 v[120:123], v[158:161], v[166:169], v[120:123]
	v_mfma_f32_16x16x32_bf16 v[116:119], v[146:149], v[174:177], v[116:119]
	v_mfma_f32_16x16x32_bf16 v[108:111], v[158:161], v[174:177], v[108:111]
	v_mfma_f32_16x16x32_bf16 v[100:103], v[146:149], v[184:187], v[100:103]
	v_mfma_f32_16x16x32_bf16 v[92:95], v[158:161], v[184:187], v[92:95]
	v_mfma_f32_16x16x32_bf16 v[84:87], v[146:149], v[192:195], v[84:87]
	v_mfma_f32_16x16x32_bf16 v[76:79], v[158:161], v[192:195], v[76:79]
	s_setprio 0
	s_barrier
	s_add_i32 s14, 0, 0x1c000
	s_add_i32 s15, s21, s16
	v_add_u32_e32 v153, s14, v140
	s_add_i32 m0, s15, 0xffffff80
	ds_read_b128 v[196:199], v153
	ds_read_b128 v[224:227], v153 offset:1024
	ds_read_b128 v[228:231], v153 offset:2048
	ds_read_b128 v[232:235], v153 offset:3072
	global_load_lds_dwordx4 v178, s[12:13] offset:128
	s_add_i32 m0, s15, 0x1f80
	s_nop 0
	global_load_lds_dwordx4 v128, s[12:13] offset:128
	s_barrier
	s_waitcnt lgkmcnt(0)
	s_setprio 1
	s_waitcnt lgkmcnt(0)
	v_mfma_f32_16x16x32_bf16 v[112:115], v[196:199], v[162:165], v[112:115]
	v_mfma_f32_16x16x32_bf16 v[104:107], v[228:231], v[162:165], v[104:107]
	v_mfma_f32_16x16x32_bf16 v[96:99], v[196:199], v[170:173], v[96:99]
	v_mfma_f32_16x16x32_bf16 v[88:91], v[228:231], v[170:173], v[88:91]
	v_mfma_f32_16x16x32_bf16 v[80:83], v[196:199], v[180:183], v[80:83]
	v_mfma_f32_16x16x32_bf16 v[72:75], v[228:231], v[180:183], v[72:75]
	v_mfma_f32_16x16x32_bf16 v[68:71], v[196:199], v[188:191], v[68:71]
	v_mfma_f32_16x16x32_bf16 v[64:67], v[228:231], v[188:191], v[64:67]
	v_mfma_f32_16x16x32_bf16 v[112:115], v[224:227], v[166:169], v[112:115]
	v_mfma_f32_16x16x32_bf16 v[104:107], v[232:235], v[166:169], v[104:107]
	v_mfma_f32_16x16x32_bf16 v[96:99], v[224:227], v[174:177], v[96:99]
	v_mfma_f32_16x16x32_bf16 v[88:91], v[232:235], v[174:177], v[88:91]
	v_mfma_f32_16x16x32_bf16 v[80:83], v[224:227], v[184:187], v[80:83]
	v_mfma_f32_16x16x32_bf16 v[72:75], v[232:235], v[184:187], v[72:75]
	v_mfma_f32_16x16x32_bf16 v[68:71], v[224:227], v[192:195], v[68:71]
	v_mfma_f32_16x16x32_bf16 v[64:67], v[232:235], v[192:195], v[64:67]
	s_setprio 0
	s_add_i32 m0, s18, 0xffffff80
	s_barrier
	ds_read_b128 v[162:165], v141 offset:49152
	ds_read_b128 v[166:169], v141 offset:50176
	ds_read_b128 v[170:173], v141 offset:51200
	ds_read_b128 v[174:177], v141 offset:52224
	ds_read_b128 v[180:183], v141 offset:53248
	ds_read_b128 v[184:187], v141 offset:54272
	ds_read_b128 v[188:191], v141 offset:55296
	ds_read_b128 v[192:195], v141 offset:56320
	global_load_lds_dwordx4 v132, s[100:101] offset:128
	s_add_i32 m0, s19, 0xffffff80
	s_nop 0
	global_load_lds_dwordx4 v130, s[100:101] offset:128
	s_barrier
	s_waitcnt lgkmcnt(0)
	s_setprio 1
	s_waitcnt lgkmcnt(0)
	v_mfma_f32_16x16x32_bf16 v[60:63], v[142:145], v[162:165], v[60:63]
	v_mfma_f32_16x16x32_bf16 v[56:59], v[154:157], v[162:165], v[56:59]
	v_mfma_f32_16x16x32_bf16 v[52:55], v[142:145], v[170:173], v[52:55]
	v_mfma_f32_16x16x32_bf16 v[44:47], v[154:157], v[170:173], v[44:47]
	v_mfma_f32_16x16x32_bf16 v[36:39], v[142:145], v[180:183], v[36:39]
	v_mfma_f32_16x16x32_bf16 v[28:31], v[154:157], v[180:183], v[28:31]
	v_mfma_f32_16x16x32_bf16 v[20:23], v[142:145], v[188:191], v[20:23]
	v_mfma_f32_16x16x32_bf16 v[12:15], v[154:157], v[188:191], v[12:15]
	v_mfma_f32_16x16x32_bf16 v[60:63], v[146:149], v[166:169], v[60:63]
	v_mfma_f32_16x16x32_bf16 v[56:59], v[158:161], v[166:169], v[56:59]
	v_mfma_f32_16x16x32_bf16 v[52:55], v[146:149], v[174:177], v[52:55]
	v_mfma_f32_16x16x32_bf16 v[44:47], v[158:161], v[174:177], v[44:47]
	v_mfma_f32_16x16x32_bf16 v[36:39], v[146:149], v[184:187], v[36:39]
	v_mfma_f32_16x16x32_bf16 v[28:31], v[158:161], v[184:187], v[28:31]
	v_mfma_f32_16x16x32_bf16 v[20:23], v[146:149], v[192:195], v[20:23]
	v_mfma_f32_16x16x32_bf16 v[12:15], v[158:161], v[192:195], v[12:15]
	s_setprio 0
	s_barrier
	s_add_u32 s12, s12, 0x20080
	s_addc_u32 s13, s13, 0
	s_add_i32 s14, s14, s16
	s_mov_b32 m0, s14
	s_nop 0
	global_load_lds_dwordx4 v178, s[12:13]
	s_add_i32 m0, s14, 0x2000
	s_nop 0
	global_load_lds_dwordx4 v128, s[12:13]
	s_waitcnt vmcnt(6)
	s_barrier
	s_setprio 1
	v_mfma_f32_16x16x32_bf16 v[48:51], v[196:199], v[162:165], v[48:51]
	v_mfma_f32_16x16x32_bf16 v[40:43], v[228:231], v[162:165], v[40:43]
	v_mfma_f32_16x16x32_bf16 v[32:35], v[196:199], v[170:173], v[32:35]
	v_mfma_f32_16x16x32_bf16 v[24:27], v[228:231], v[170:173], v[24:27]
	v_mfma_f32_16x16x32_bf16 v[16:19], v[196:199], v[180:183], v[16:19]
	v_mfma_f32_16x16x32_bf16 v[8:11], v[228:231], v[180:183], v[8:11]
	v_mfma_f32_16x16x32_bf16 v[4:7], v[196:199], v[188:191], v[4:7]
	v_mfma_f32_16x16x32_bf16 v[0:3], v[228:231], v[188:191], v[0:3]
	v_mfma_f32_16x16x32_bf16 v[48:51], v[224:227], v[166:169], v[48:51]
	v_mfma_f32_16x16x32_bf16 v[40:43], v[232:235], v[166:169], v[40:43]
	v_mfma_f32_16x16x32_bf16 v[32:35], v[224:227], v[174:177], v[32:35]
	v_mfma_f32_16x16x32_bf16 v[24:27], v[232:235], v[174:177], v[24:27]
	v_mfma_f32_16x16x32_bf16 v[16:19], v[224:227], v[184:187], v[16:19]
	v_mfma_f32_16x16x32_bf16 v[8:11], v[232:235], v[184:187], v[8:11]
	v_mfma_f32_16x16x32_bf16 v[4:7], v[224:227], v[192:195], v[4:7]
	v_mfma_f32_16x16x32_bf16 v[0:3], v[232:235], v[192:195], v[0:3]
	s_setprio 0
	s_add_i32 s20, s20, 2
	s_add_u32 s10, s10, 0x100
	s_addc_u32 s11, s11, 0
	s_cmp_gt_u32 s20, 5
	s_barrier
	s_cbranch_scc0 .LBB0_943
	v_readlane_b32 s6, v254, 23
	s_or_b32 s6, s17, s6
	v_cvt_pk_bf16_f32 v124, v124, v125
	v_cvt_pk_bf16_f32 v125, v126, v127
	v_cvt_pk_bf16_f32 v126, v120, v121
	v_cvt_pk_bf16_f32 v127, v122, v123
	s_nop 0
	v_or_b32_e32 v132, s6, v139
	v_readlane_b32 s6, v254, 25
	v_lshlrev_b32_e32 v178, 1, v132
	s_nop 0
	v_add_u32_e32 v128, s6, v138
	v_ashrrev_i32_e32 v129, 31, v128
	v_lshlrev_b64 v[130:131], 12, v[128:129]
	v_lshl_add_u64 v[130:131], s[4:5], 0, v[130:131]
	v_lshl_add_u64 v[130:131], v[130:131], 0, v[178:179]
	global_store_dwordx4 v[130:131], v[124:127], off
	v_cvt_pk_bf16_f32 v112, v112, v113
	v_cvt_pk_bf16_f32 v113, v114, v115
	v_cvt_pk_bf16_f32 v114, v104, v105
	v_or_b32_e32 v104, 16, v128
	v_ashrrev_i32_e32 v105, 31, v104
	v_lshlrev_b64 v[104:105], 12, v[104:105]
	v_lshl_add_u64 v[104:105], s[4:5], 0, v[104:105]
	v_cvt_pk_bf16_f32 v115, v106, v107
	global_store_dwordx4 v[130:131], v[112:115], off offset:256
	s_nop 1
	v_lshl_add_u64 v[112:113], v[104:105], 0, v[178:179]
	v_cvt_pk_bf16_f32 v104, v116, v117
	v_cvt_pk_bf16_f32 v105, v118, v119
	v_cvt_pk_bf16_f32 v106, v108, v109
	v_cvt_pk_bf16_f32 v107, v110, v111
	global_store_dwordx4 v[112:113], v[104:107], off
	v_cvt_pk_bf16_f32 v96, v96, v97
	v_cvt_pk_bf16_f32 v97, v98, v99
	v_cvt_pk_bf16_f32 v98, v88, v89
	v_or_b32_e32 v88, 32, v128
	v_ashrrev_i32_e32 v89, 31, v88
	v_lshlrev_b64 v[88:89], 12, v[88:89]
	v_lshl_add_u64 v[88:89], s[4:5], 0, v[88:89]
	v_cvt_pk_bf16_f32 v99, v90, v91
	global_store_dwordx4 v[112:113], v[96:99], off offset:256
	s_nop 1
	v_lshl_add_u64 v[96:97], v[88:89], 0, v[178:179]
	v_cvt_pk_bf16_f32 v88, v100, v101
	v_cvt_pk_bf16_f32 v89, v102, v103
	v_cvt_pk_bf16_f32 v90, v92, v93
	v_cvt_pk_bf16_f32 v91, v94, v95
	global_store_dwordx4 v[96:97], v[88:91], off
	v_cvt_pk_bf16_f32 v80, v80, v81
	v_cvt_pk_bf16_f32 v81, v82, v83
	v_cvt_pk_bf16_f32 v82, v72, v73
	v_or_b32_e32 v72, 48, v128
	v_ashrrev_i32_e32 v73, 31, v72
	v_lshlrev_b64 v[72:73], 12, v[72:73]
	v_lshl_add_u64 v[72:73], s[4:5], 0, v[72:73]
	v_cvt_pk_bf16_f32 v83, v74, v75
	global_store_dwordx4 v[96:97], v[80:83], off offset:256
	s_nop 1
	v_lshl_add_u64 v[80:81], v[72:73], 0, v[178:179]
	v_cvt_pk_bf16_f32 v72, v84, v85
	v_cvt_pk_bf16_f32 v73, v86, v87
	v_cvt_pk_bf16_f32 v74, v76, v77
	v_cvt_pk_bf16_f32 v75, v78, v79
	global_store_dwordx4 v[80:81], v[72:75], off
	v_cvt_pk_bf16_f32 v68, v68, v69
	v_cvt_pk_bf16_f32 v69, v70, v71
	v_cvt_pk_bf16_f32 v70, v64, v65
	v_add_u32_e32 v64, 0x80, v128
	v_ashrrev_i32_e32 v65, 31, v64
	v_lshlrev_b64 v[64:65], 12, v[64:65]
	v_lshl_add_u64 v[64:65], s[4:5], 0, v[64:65]
	v_lshl_add_u64 v[64:65], v[64:65], 0, v[178:179]
	v_cvt_pk_bf16_f32 v71, v66, v67
	global_store_dwordx4 v[80:81], v[68:71], off offset:256
	v_cvt_pk_bf16_f32 v60, v60, v61
	v_cvt_pk_bf16_f32 v61, v62, v63
	v_cvt_pk_bf16_f32 v62, v56, v57
	v_cvt_pk_bf16_f32 v63, v58, v59
	global_store_dwordx4 v[64:65], v[60:63], off
	v_cvt_pk_bf16_f32 v48, v48, v49
	v_cvt_pk_bf16_f32 v49, v50, v51
	v_cvt_pk_bf16_f32 v50, v40, v41
	v_add_u32_e32 v40, 0x90, v128
	v_ashrrev_i32_e32 v41, 31, v40
	v_lshlrev_b64 v[40:41], 12, v[40:41]
	v_lshl_add_u64 v[40:41], s[4:5], 0, v[40:41]
	v_cvt_pk_bf16_f32 v51, v42, v43
	global_store_dwordx4 v[64:65], v[48:51], off offset:256
	s_nop 1
	v_lshl_add_u64 v[48:49], v[40:41], 0, v[178:179]
	v_cvt_pk_bf16_f32 v40, v52, v53
	v_cvt_pk_bf16_f32 v41, v54, v55
	v_cvt_pk_bf16_f32 v42, v44, v45
	v_cvt_pk_bf16_f32 v43, v46, v47
	global_store_dwordx4 v[48:49], v[40:43], off
	v_cvt_pk_bf16_f32 v32, v32, v33
	v_cvt_pk_bf16_f32 v33, v34, v35
	v_cvt_pk_bf16_f32 v34, v24, v25
	v_add_u32_e32 v24, 0xa0, v128
	v_ashrrev_i32_e32 v25, 31, v24
	v_lshlrev_b64 v[24:25], 12, v[24:25]
	v_lshl_add_u64 v[24:25], s[4:5], 0, v[24:25]
	v_cvt_pk_bf16_f32 v35, v26, v27
	global_store_dwordx4 v[48:49], v[32:35], off offset:256
	s_nop 1
	v_lshl_add_u64 v[32:33], v[24:25], 0, v[178:179]
	v_cvt_pk_bf16_f32 v24, v36, v37
	v_cvt_pk_bf16_f32 v25, v38, v39
	v_cvt_pk_bf16_f32 v26, v28, v29
	v_cvt_pk_bf16_f32 v27, v30, v31
	global_store_dwordx4 v[32:33], v[24:27], off
	v_cvt_pk_bf16_f32 v16, v16, v17
	v_cvt_pk_bf16_f32 v17, v18, v19
	v_cvt_pk_bf16_f32 v18, v8, v9
	v_add_u32_e32 v8, 0xb0, v128
	v_ashrrev_i32_e32 v9, 31, v8
	v_lshlrev_b64 v[8:9], 12, v[8:9]
	v_lshl_add_u64 v[8:9], s[4:5], 0, v[8:9]
	v_cvt_pk_bf16_f32 v19, v10, v11
	global_store_dwordx4 v[32:33], v[16:19], off offset:256
	v_readlane_b32 s4, v255, 8
	s_nop 0
	v_lshl_add_u64 v[16:17], v[8:9], 0, v[178:179]
	v_cvt_pk_bf16_f32 v8, v20, v21
	v_cvt_pk_bf16_f32 v9, v22, v23
	v_cvt_pk_bf16_f32 v10, v12, v13
	v_cvt_pk_bf16_f32 v11, v14, v15
	global_store_dwordx4 v[16:17], v[8:11], off
	v_cvt_pk_bf16_f32 v4, v4, v5
	v_cvt_pk_bf16_f32 v5, v6, v7
	v_cvt_pk_bf16_f32 v6, v0, v1
	v_cvt_pk_bf16_f32 v7, v2, v3
	global_store_dwordx4 v[16:17], v[4:7], off offset:256
	s_waitcnt vmcnt(0)
	s_cmp_lt_u32 s4, 4
	s_cbranch_scc0 .LBB0_946
	s_barrier

.LBB0_1077:
	s_add_u32 s18, s16, 0x100
	s_addc_u32 s19, s17, 0
	s_add_i32 s66, 0, 0x10000
	v_add_u32_e32 v140, s66, v157
	ds_read_b128 v[128:131], v140
	ds_read_b128 v[132:135], v140 offset:1024
	ds_read_b128 v[136:139], v140 offset:2048
	ds_read_b128 v[140:143], v140 offset:3072
	s_cmp_eq_u32 s63, 28
	s_cselect_b32 s23, s13, s19
	s_cselect_b32 s22, s12, s18
	s_cselect_b32 s21, s15, s62
	s_cselect_b32 s20, s14, s5
	v_lshl_add_u64 v[154:155], s[16:17], 0, v[148:149]
	s_add_i32 m0, s29, 0xc000
	ds_read_b128 v[150:153], v159
	ds_read_b128 v[160:163], v159 offset:1024
	ds_read_b128 v[164:167], v159 offset:2048
	ds_read_b128 v[168:171], v159 offset:3072
	ds_read_b128 v[172:175], v159 offset:4096
	ds_read_b128 v[180:183], v159 offset:5120
	ds_read_b128 v[184:187], v159 offset:6144
	ds_read_b128 v[188:191], v159 offset:7168
	global_load_lds_dwordx4 v[154:155], off
	v_lshl_add_u64 v[154:155], s[16:17], 0, v[146:147]
	s_add_i32 m0, s29, 0xe000
	s_nop 0
	global_load_lds_dwordx4 v[154:155], off
	s_waitcnt lgkmcnt(8)
	s_barrier
	s_waitcnt lgkmcnt(0)
	s_setprio 1
	s_waitcnt lgkmcnt(0)
	v_mfma_f32_16x16x32_bf16 v[124:127], v[128:131], v[150:153], v[124:127]
	v_mfma_f32_16x16x32_bf16 v[120:123], v[136:139], v[150:153], v[120:123]
	v_mfma_f32_16x16x32_bf16 v[108:111], v[128:131], v[164:167], v[108:111]
	v_mfma_f32_16x16x32_bf16 v[104:107], v[136:139], v[164:167], v[104:107]
	v_mfma_f32_16x16x32_bf16 v[92:95], v[128:131], v[172:175], v[92:95]
	v_mfma_f32_16x16x32_bf16 v[88:91], v[136:139], v[172:175], v[88:91]
	v_mfma_f32_16x16x32_bf16 v[76:79], v[128:131], v[184:187], v[76:79]
	v_mfma_f32_16x16x32_bf16 v[72:75], v[136:139], v[184:187], v[72:75]
	v_mfma_f32_16x16x32_bf16 v[124:127], v[132:135], v[160:163], v[124:127]
	v_mfma_f32_16x16x32_bf16 v[120:123], v[140:143], v[160:163], v[120:123]
	v_mfma_f32_16x16x32_bf16 v[108:111], v[132:135], v[168:171], v[108:111]
	v_mfma_f32_16x16x32_bf16 v[104:107], v[140:143], v[168:171], v[104:107]
	v_mfma_f32_16x16x32_bf16 v[92:95], v[132:135], v[180:183], v[92:95]
	v_mfma_f32_16x16x32_bf16 v[88:91], v[140:143], v[180:183], v[88:91]
	v_mfma_f32_16x16x32_bf16 v[76:79], v[132:135], v[188:191], v[76:79]
	v_mfma_f32_16x16x32_bf16 v[72:75], v[140:143], v[188:191], v[72:75]
	s_setprio 0
	s_barrier
	s_add_i32 s67, 0, 0x14000
	v_add_u32_e32 v154, s67, v157
	s_add_i32 s16, s66, s28
	ds_read_b128 v[192:195], v154
	ds_read_b128 v[196:199], v154 offset:1024
	ds_read_b128 v[204:207], v154 offset:2048
	ds_read_b128 v[212:215], v154 offset:3072
	s_mov_b32 m0, s16
	global_load_lds_dwordx4 v178, s[20:21]
	s_add_i32 m0, s16, 0x2000
	s_nop 0
	global_load_lds_dwordx4 v144, s[20:21]
	s_barrier
	s_waitcnt lgkmcnt(0)
	s_setprio 1
	s_waitcnt lgkmcnt(0)
	v_mfma_f32_16x16x32_bf16 v[116:119], v[192:195], v[150:153], v[116:119]
	v_mfma_f32_16x16x32_bf16 v[112:115], v[204:207], v[150:153], v[112:115]
	v_mfma_f32_16x16x32_bf16 v[100:103], v[192:195], v[164:167], v[100:103]
	v_mfma_f32_16x16x32_bf16 v[96:99], v[204:207], v[164:167], v[96:99]
	v_mfma_f32_16x16x32_bf16 v[84:87], v[192:195], v[172:175], v[84:87]
	v_mfma_f32_16x16x32_bf16 v[80:83], v[204:207], v[172:175], v[80:83]
	v_mfma_f32_16x16x32_bf16 v[68:71], v[192:195], v[184:187], v[68:71]
	v_mfma_f32_16x16x32_bf16 v[64:67], v[204:207], v[184:187], v[64:67]
	v_mfma_f32_16x16x32_bf16 v[116:119], v[196:199], v[160:163], v[116:119]
	v_mfma_f32_16x16x32_bf16 v[112:115], v[212:215], v[160:163], v[112:115]
	v_mfma_f32_16x16x32_bf16 v[100:103], v[196:199], v[168:171], v[100:103]
	v_mfma_f32_16x16x32_bf16 v[96:99], v[212:215], v[168:171], v[96:99]
	v_mfma_f32_16x16x32_bf16 v[84:87], v[196:199], v[180:183], v[84:87]
	v_mfma_f32_16x16x32_bf16 v[80:83], v[212:215], v[180:183], v[80:83]
	v_mfma_f32_16x16x32_bf16 v[68:71], v[196:199], v[188:191], v[68:71]
	v_mfma_f32_16x16x32_bf16 v[64:67], v[212:215], v[188:191], v[64:67]
	s_setprio 0
	s_mov_b32 m0, s29
	s_mov_b64 s[100:101], s[22:23]
	s_barrier
	ds_read_b128 v[150:153], v159 offset:16384
	ds_read_b128 v[160:163], v159 offset:17408
	ds_read_b128 v[164:167], v159 offset:18432
	ds_read_b128 v[168:171], v159 offset:19456
	ds_read_b128 v[172:175], v159 offset:20480
	ds_read_b128 v[180:183], v159 offset:21504
	ds_read_b128 v[184:187], v159 offset:22528
	ds_read_b128 v[188:191], v159 offset:23552
	global_load_lds_dwordx4 v178, s[22:23]
	s_mov_b64 s[100:101], s[22:23]
	s_mov_b32 m0, s30
	s_nop 0
	global_load_lds_dwordx4 v144, s[22:23]
	s_barrier
	s_waitcnt lgkmcnt(0)
	s_setprio 1
	s_waitcnt lgkmcnt(0)
	v_mfma_f32_16x16x32_bf16 v[60:63], v[128:131], v[150:153], v[60:63]
	v_mfma_f32_16x16x32_bf16 v[56:59], v[136:139], v[150:153], v[56:59]
	v_mfma_f32_16x16x32_bf16 v[44:47], v[128:131], v[164:167], v[44:47]
	v_mfma_f32_16x16x32_bf16 v[40:43], v[136:139], v[164:167], v[40:43]
	v_mfma_f32_16x16x32_bf16 v[28:31], v[128:131], v[172:175], v[28:31]
	v_mfma_f32_16x16x32_bf16 v[24:27], v[136:139], v[172:175], v[24:27]
	v_mfma_f32_16x16x32_bf16 v[12:15], v[128:131], v[184:187], v[12:15]
	v_mfma_f32_16x16x32_bf16 v[8:11], v[136:139], v[184:187], v[8:11]
	v_mfma_f32_16x16x32_bf16 v[60:63], v[132:135], v[160:163], v[60:63]
	v_mfma_f32_16x16x32_bf16 v[56:59], v[140:143], v[160:163], v[56:59]
	v_mfma_f32_16x16x32_bf16 v[44:47], v[132:135], v[168:171], v[44:47]
	v_mfma_f32_16x16x32_bf16 v[40:43], v[140:143], v[168:171], v[40:43]
	v_mfma_f32_16x16x32_bf16 v[28:31], v[132:135], v[180:183], v[28:31]
	v_mfma_f32_16x16x32_bf16 v[24:27], v[140:143], v[180:183], v[24:27]
	v_mfma_f32_16x16x32_bf16 v[12:15], v[132:135], v[188:191], v[12:15]
	v_mfma_f32_16x16x32_bf16 v[8:11], v[140:143], v[188:191], v[8:11]
	s_setprio 0
	s_barrier
	s_add_u32 s16, s20, 0x80000
	s_addc_u32 s17, s21, 0
	s_add_i32 s66, s67, s28
	s_mov_b32 m0, s66
	s_nop 0
	global_load_lds_dwordx4 v178, s[16:17]
	s_add_i32 m0, s66, 0x2000
	s_nop 0
	global_load_lds_dwordx4 v144, s[16:17]
	s_waitcnt vmcnt(6)
	s_barrier
	s_setprio 1
	v_mfma_f32_16x16x32_bf16 v[52:55], v[192:195], v[150:153], v[52:55]
	v_mfma_f32_16x16x32_bf16 v[48:51], v[204:207], v[150:153], v[48:51]
	v_mfma_f32_16x16x32_bf16 v[36:39], v[192:195], v[164:167], v[36:39]
	v_mfma_f32_16x16x32_bf16 v[32:35], v[204:207], v[164:167], v[32:35]
	v_mfma_f32_16x16x32_bf16 v[20:23], v[192:195], v[172:175], v[20:23]
	v_mfma_f32_16x16x32_bf16 v[16:19], v[204:207], v[172:175], v[16:19]
	v_mfma_f32_16x16x32_bf16 v[4:7], v[192:195], v[184:187], v[4:7]
	v_mfma_f32_16x16x32_bf16 v[0:3], v[204:207], v[184:187], v[0:3]
	v_mfma_f32_16x16x32_bf16 v[52:55], v[196:199], v[160:163], v[52:55]
	v_mfma_f32_16x16x32_bf16 v[48:51], v[212:215], v[160:163], v[48:51]
	v_mfma_f32_16x16x32_bf16 v[36:39], v[196:199], v[168:171], v[36:39]
	v_mfma_f32_16x16x32_bf16 v[32:35], v[212:215], v[168:171], v[32:35]
	v_mfma_f32_16x16x32_bf16 v[20:23], v[196:199], v[180:183], v[20:23]
	v_mfma_f32_16x16x32_bf16 v[16:19], v[212:215], v[180:183], v[16:19]
	v_mfma_f32_16x16x32_bf16 v[4:7], v[196:199], v[188:191], v[4:7]
	v_mfma_f32_16x16x32_bf16 v[0:3], v[212:215], v[188:191], v[0:3]
	s_setprio 0
	s_add_i32 s66, 0, 0x18000
	v_add_u32_e32 v140, s66, v157
	s_barrier
	ds_read_b128 v[128:131], v140
	ds_read_b128 v[132:135], v140 offset:1024
	ds_read_b128 v[136:139], v140 offset:2048
	ds_read_b128 v[140:143], v140 offset:3072
	s_add_u32 s16, s22, 0x80000
	s_addc_u32 s17, s23, 0
	s_mov_b32 m0, s31
	ds_read_b128 v[150:153], v159 offset:32768
	ds_read_b128 v[160:163], v159 offset:33792
	ds_read_b128 v[164:167], v159 offset:34816
	ds_read_b128 v[168:171], v159 offset:35840
	ds_read_b128 v[172:175], v159 offset:36864
	ds_read_b128 v[180:183], v159 offset:37888
	ds_read_b128 v[184:187], v159 offset:38912
	ds_read_b128 v[188:191], v159 offset:39936
	global_load_lds_dwordx4 v178, s[16:17]
	s_mov_b32 m0, s34
	s_nop 0
	global_load_lds_dwordx4 v144, s[16:17]
	s_waitcnt lgkmcnt(8)
	s_barrier
	s_waitcnt lgkmcnt(0)
	s_setprio 1
	s_waitcnt lgkmcnt(0)
	v_mfma_f32_16x16x32_bf16 v[124:127], v[128:131], v[150:153], v[124:127]
	v_mfma_f32_16x16x32_bf16 v[120:123], v[136:139], v[150:153], v[120:123]
	v_mfma_f32_16x16x32_bf16 v[108:111], v[128:131], v[164:167], v[108:111]
	v_mfma_f32_16x16x32_bf16 v[104:107], v[136:139], v[164:167], v[104:107]
	v_mfma_f32_16x16x32_bf16 v[92:95], v[128:131], v[172:175], v[92:95]
	v_mfma_f32_16x16x32_bf16 v[88:91], v[136:139], v[172:175], v[88:91]
	v_mfma_f32_16x16x32_bf16 v[76:79], v[128:131], v[184:187], v[76:79]
	v_mfma_f32_16x16x32_bf16 v[72:75], v[136:139], v[184:187], v[72:75]
	v_mfma_f32_16x16x32_bf16 v[124:127], v[132:135], v[160:163], v[124:127]
	v_mfma_f32_16x16x32_bf16 v[120:123], v[140:143], v[160:163], v[120:123]
	v_mfma_f32_16x16x32_bf16 v[108:111], v[132:135], v[168:171], v[108:111]
	v_mfma_f32_16x16x32_bf16 v[104:107], v[140:143], v[168:171], v[104:107]
	v_mfma_f32_16x16x32_bf16 v[92:95], v[132:135], v[180:183], v[92:95]
	v_mfma_f32_16x16x32_bf16 v[88:91], v[140:143], v[180:183], v[88:91]
	v_mfma_f32_16x16x32_bf16 v[76:79], v[132:135], v[188:191], v[76:79]
	v_mfma_f32_16x16x32_bf16 v[72:75], v[140:143], v[188:191], v[72:75]
	s_setprio 0
	s_barrier
	s_add_i32 s22, 0, 0x1c000
	s_add_i32 s16, s66, s28
	v_add_u32_e32 v212, s22, v157
	s_add_i32 m0, s16, 0xffffff80
	ds_read_b128 v[192:195], v212
	ds_read_b128 v[196:199], v212 offset:1024
	ds_read_b128 v[204:207], v212 offset:2048
	ds_read_b128 v[212:215], v212 offset:3072
	global_load_lds_dwordx4 v178, s[20:21] offset:128
	s_add_i32 m0, s16, 0x1f80
	s_nop 0
	global_load_lds_dwordx4 v144, s[20:21] offset:128
	s_barrier
	s_waitcnt lgkmcnt(0)
	s_setprio 1
	s_waitcnt lgkmcnt(0)
	v_mfma_f32_16x16x32_bf16 v[116:119], v[192:195], v[150:153], v[116:119]
	v_mfma_f32_16x16x32_bf16 v[112:115], v[204:207], v[150:153], v[112:115]
	v_mfma_f32_16x16x32_bf16 v[100:103], v[192:195], v[164:167], v[100:103]
	v_mfma_f32_16x16x32_bf16 v[96:99], v[204:207], v[164:167], v[96:99]
	v_mfma_f32_16x16x32_bf16 v[84:87], v[192:195], v[172:175], v[84:87]
	v_mfma_f32_16x16x32_bf16 v[80:83], v[204:207], v[172:175], v[80:83]
	v_mfma_f32_16x16x32_bf16 v[68:71], v[192:195], v[184:187], v[68:71]
	v_mfma_f32_16x16x32_bf16 v[64:67], v[204:207], v[184:187], v[64:67]
	v_mfma_f32_16x16x32_bf16 v[116:119], v[196:199], v[160:163], v[116:119]
	v_mfma_f32_16x16x32_bf16 v[112:115], v[212:215], v[160:163], v[112:115]
	v_mfma_f32_16x16x32_bf16 v[100:103], v[196:199], v[168:171], v[100:103]
	v_mfma_f32_16x16x32_bf16 v[96:99], v[212:215], v[168:171], v[96:99]
	v_mfma_f32_16x16x32_bf16 v[84:87], v[196:199], v[180:183], v[84:87]
	v_mfma_f32_16x16x32_bf16 v[80:83], v[212:215], v[180:183], v[80:83]
	v_mfma_f32_16x16x32_bf16 v[68:71], v[196:199], v[188:191], v[68:71]
	v_mfma_f32_16x16x32_bf16 v[64:67], v[212:215], v[188:191], v[64:67]
	s_setprio 0
	s_add_i32 m0, s56, 0xffffff80
	s_barrier
	ds_read_b128 v[150:153], v159 offset:49152
	ds_read_b128 v[160:163], v159 offset:50176
	ds_read_b128 v[164:167], v159 offset:51200
	ds_read_b128 v[168:171], v159 offset:52224
	ds_read_b128 v[172:175], v159 offset:53248
	ds_read_b128 v[180:183], v159 offset:54272
	ds_read_b128 v[184:187], v159 offset:55296
	ds_read_b128 v[188:191], v159 offset:56320
	global_load_lds_dwordx4 v178, s[100:101] offset:128
	s_add_i32 m0, s57, 0xffffff80
	s_nop 0
	global_load_lds_dwordx4 v144, s[100:101] offset:128
	s_barrier
	s_waitcnt lgkmcnt(0)
	s_setprio 1
	s_waitcnt lgkmcnt(0)
	v_mfma_f32_16x16x32_bf16 v[60:63], v[128:131], v[150:153], v[60:63]
	v_mfma_f32_16x16x32_bf16 v[56:59], v[136:139], v[150:153], v[56:59]
	v_mfma_f32_16x16x32_bf16 v[44:47], v[128:131], v[164:167], v[44:47]
	v_mfma_f32_16x16x32_bf16 v[40:43], v[136:139], v[164:167], v[40:43]
	v_mfma_f32_16x16x32_bf16 v[28:31], v[128:131], v[172:175], v[28:31]
	v_mfma_f32_16x16x32_bf16 v[24:27], v[136:139], v[172:175], v[24:27]
	v_mfma_f32_16x16x32_bf16 v[12:15], v[128:131], v[184:187], v[12:15]
	v_mfma_f32_16x16x32_bf16 v[8:11], v[136:139], v[184:187], v[8:11]
	v_mfma_f32_16x16x32_bf16 v[60:63], v[132:135], v[160:163], v[60:63]
	v_mfma_f32_16x16x32_bf16 v[56:59], v[140:143], v[160:163], v[56:59]
	v_mfma_f32_16x16x32_bf16 v[44:47], v[132:135], v[168:171], v[44:47]
	v_mfma_f32_16x16x32_bf16 v[40:43], v[140:143], v[168:171], v[40:43]
	v_mfma_f32_16x16x32_bf16 v[28:31], v[132:135], v[180:183], v[28:31]
	v_mfma_f32_16x16x32_bf16 v[24:27], v[140:143], v[180:183], v[24:27]
	v_mfma_f32_16x16x32_bf16 v[12:15], v[132:135], v[188:191], v[12:15]
	v_mfma_f32_16x16x32_bf16 v[8:11], v[140:143], v[188:191], v[8:11]
	s_setprio 0
	s_barrier
	s_add_u32 s16, s20, 0x80080
	s_addc_u32 s17, s21, 0
	s_add_i32 s20, s22, s28
	s_mov_b32 m0, s20
	s_nop 0
	global_load_lds_dwordx4 v178, s[16:17]
	s_add_i32 m0, s20, 0x2000
	s_nop 0
	global_load_lds_dwordx4 v144, s[16:17]
	s_waitcnt vmcnt(6)
	s_barrier
	s_setprio 1
	v_mfma_f32_16x16x32_bf16 v[52:55], v[192:195], v[150:153], v[52:55]
	v_mfma_f32_16x16x32_bf16 v[48:51], v[204:207], v[150:153], v[48:51]
	v_mfma_f32_16x16x32_bf16 v[36:39], v[192:195], v[164:167], v[36:39]
	v_mfma_f32_16x16x32_bf16 v[32:35], v[204:207], v[164:167], v[32:35]
	v_mfma_f32_16x16x32_bf16 v[20:23], v[192:195], v[172:175], v[20:23]
	v_mfma_f32_16x16x32_bf16 v[16:19], v[204:207], v[172:175], v[16:19]
	v_mfma_f32_16x16x32_bf16 v[4:7], v[192:195], v[184:187], v[4:7]
	v_mfma_f32_16x16x32_bf16 v[0:3], v[204:207], v[184:187], v[0:3]
	v_mfma_f32_16x16x32_bf16 v[52:55], v[196:199], v[160:163], v[52:55]
	v_mfma_f32_16x16x32_bf16 v[48:51], v[212:215], v[160:163], v[48:51]
	v_mfma_f32_16x16x32_bf16 v[36:39], v[196:199], v[168:171], v[36:39]
	v_mfma_f32_16x16x32_bf16 v[32:35], v[212:215], v[168:171], v[32:35]
	v_mfma_f32_16x16x32_bf16 v[20:23], v[196:199], v[180:183], v[20:23]
	v_mfma_f32_16x16x32_bf16 v[16:19], v[212:215], v[180:183], v[16:19]
	v_mfma_f32_16x16x32_bf16 v[4:7], v[196:199], v[188:191], v[4:7]
	v_mfma_f32_16x16x32_bf16 v[0:3], v[212:215], v[188:191], v[0:3]
	s_setprio 0
	s_add_i32 s63, s63, 2
	s_add_u32 s5, s5, 0x100
	s_addc_u32 s62, s62, 0
	s_cmp_gt_u32 s63, 29
	s_mov_b64 s[16:17], s[18:19]
	s_barrier
	s_cbranch_scc0 .LBB0_1077
	s_lshl_b32 s5, s60, 8
	s_add_i32 s12, s5, 0xfffff000
	s_ashr_i32 s12, s12, 11
	s_add_i32 s12, s12, 1
	s_cmp_lt_i32 s60, 16
	s_cselect_b32 s12, 0, s12
	v_add_u32_e32 v154, s5, v156
	v_lshl_or_b32 v152, s61, 8, v158
	s_mul_hi_i32 s15, s12, 0xc000
	s_mul_i32 s14, s12, 0xc000
	v_readlane_b32 s12, v254, 59
	v_readlane_b32 s13, v254, 63
	v_ashrrev_i32_e32 v155, 31, v154
	s_cselect_b32 s13, s12, s13
	v_readlane_b32 s12, v254, 61
	v_readlane_b32 s16, v255, 1
	v_ashrrev_i32_e32 v153, 31, v152
	v_lshlrev_b64 v[150:151], 11, v[154:155]
	s_cselect_b32 s12, s12, s16
	s_add_u32 s14, s35, s14
	v_lshl_add_u64 v[150:151], v[150:151], 0, v[152:153]
	s_addc_u32 s15, s39, s15
	v_lshlrev_b64 v[150:151], 2, v[150:151]
	v_lshl_add_u64 v[128:129], v[152:153], 2, s[14:15]
	v_lshl_add_u64 v[166:167], s[12:13], 0, v[150:151]
	global_load_dwordx4 v[140:143], v[128:129], off
	global_load_dwordx4 v[136:139], v[128:129], off offset:64
	global_load_dwordx4 v[132:135], v[128:129], off offset:512
	s_nop 0
	global_load_dwordx4 v[128:131], v[128:129], off offset:576
	v_readlane_b32 s68, v252, 37
	global_load_dwordx4 v[160:163], v[166:167], off
	v_readlane_b32 s82, v252, 51
	v_readlane_b32 s83, v252, 52
	s_mov_b64 s[14:15], 0x100000
	s_and_b64 vcc, exec, s[10:11]
	v_lshl_add_u64 v[164:165], s[82:83], 0, v[150:151]
	s_mov_b32 s61, s59
	s_mov_b32 s60, s4
	s_mov_b64 s[18:19], s[6:7]
	s_mov_b64 s[16:17], s[8:9]
	v_readlane_b32 s69, v252, 38
	v_readlane_b32 s70, v252, 39
	v_readlane_b32 s71, v252, 40
	v_readlane_b32 s72, v252, 41
	v_readlane_b32 s73, v252, 42
	v_readlane_b32 s74, v252, 43
	v_readlane_b32 s75, v252, 44
	v_readlane_b32 s76, v252, 45
	v_readlane_b32 s77, v252, 46
	v_readlane_b32 s78, v252, 47
	v_readlane_b32 s79, v252, 48
	v_readlane_b32 s80, v252, 49
	v_readlane_b32 s81, v252, 50
	s_waitcnt vmcnt(0)
	v_pk_fma_f32 v[126:127], v[126:127], v[142:143], v[162:163]
	v_pk_fma_f32 v[124:125], v[124:125], v[140:141], v[160:161]
	global_store_dwordx4 v[164:165], v[124:127], off
	global_load_dwordx4 v[124:127], v[166:167], off offset:64
	s_waitcnt vmcnt(0)
	v_pk_fma_f32 v[122:123], v[122:123], v[138:139], v[126:127]
	v_pk_fma_f32 v[120:121], v[120:121], v[136:137], v[124:125]
	global_store_dwordx4 v[164:165], v[120:123], off offset:64
	global_load_dwordx4 v[120:123], v[166:167], off offset:512
	s_waitcnt vmcnt(0)
	v_pk_fma_f32 v[118:119], v[118:119], v[134:135], v[122:123]
	v_pk_fma_f32 v[116:117], v[116:117], v[132:133], v[120:121]
	global_store_dwordx4 v[164:165], v[116:119], off offset:512
	global_load_dwordx4 v[116:119], v[166:167], off offset:576
	s_waitcnt vmcnt(0)
	v_pk_fma_f32 v[114:115], v[114:115], v[130:131], v[118:119]
	v_pk_fma_f32 v[112:113], v[112:113], v[128:129], v[116:117]
	global_store_dwordx4 v[164:165], v[112:115], off offset:576
	s_nop 1
	v_or_b32_e32 v112, 16, v154
	v_ashrrev_i32_e32 v113, 31, v112
	v_lshlrev_b64 v[112:113], 11, v[112:113]
	v_lshl_add_u64 v[112:113], v[112:113], 0, v[152:153]
	v_lshlrev_b64 v[112:113], 2, v[112:113]
	v_lshl_add_u64 v[118:119], s[12:13], 0, v[112:113]
	v_lshl_add_u64 v[116:117], s[82:83], 0, v[112:113]
	global_load_dwordx4 v[112:115], v[118:119], off
	s_waitcnt vmcnt(0)
	v_pk_fma_f32 v[110:111], v[110:111], v[142:143], v[114:115]
	v_pk_fma_f32 v[108:109], v[108:109], v[140:141], v[112:113]
	global_store_dwordx4 v[116:117], v[108:111], off
	global_load_dwordx4 v[108:111], v[118:119], off offset:64
	s_waitcnt vmcnt(0)
	v_pk_fma_f32 v[106:107], v[106:107], v[138:139], v[110:111]
	v_pk_fma_f32 v[104:105], v[104:105], v[136:137], v[108:109]
	global_store_dwordx4 v[116:117], v[104:107], off offset:64
	global_load_dwordx4 v[104:107], v[118:119], off offset:512
	s_waitcnt vmcnt(0)
	v_pk_fma_f32 v[102:103], v[102:103], v[134:135], v[106:107]
	v_pk_fma_f32 v[100:101], v[100:101], v[132:133], v[104:105]
	global_store_dwordx4 v[116:117], v[100:103], off offset:512
	global_load_dwordx4 v[100:103], v[118:119], off offset:576
	s_waitcnt vmcnt(0)
	v_pk_fma_f32 v[98:99], v[98:99], v[130:131], v[102:103]
	v_pk_fma_f32 v[96:97], v[96:97], v[128:129], v[100:101]
	global_store_dwordx4 v[116:117], v[96:99], off offset:576
	s_nop 1
	v_or_b32_e32 v96, 32, v154
	v_ashrrev_i32_e32 v97, 31, v96
	v_lshlrev_b64 v[96:97], 11, v[96:97]
	v_lshl_add_u64 v[96:97], v[96:97], 0, v[152:153]
	v_lshlrev_b64 v[96:97], 2, v[96:97]
	v_lshl_add_u64 v[102:103], s[12:13], 0, v[96:97]
	v_lshl_add_u64 v[100:101], s[82:83], 0, v[96:97]
	global_load_dwordx4 v[96:99], v[102:103], off
	s_waitcnt vmcnt(0)
	v_pk_fma_f32 v[94:95], v[94:95], v[142:143], v[98:99]
	v_pk_fma_f32 v[92:93], v[92:93], v[140:141], v[96:97]
	global_store_dwordx4 v[100:101], v[92:95], off
	global_load_dwordx4 v[92:95], v[102:103], off offset:64
	s_waitcnt vmcnt(0)
	v_pk_fma_f32 v[90:91], v[90:91], v[138:139], v[94:95]
	v_pk_fma_f32 v[88:89], v[88:89], v[136:137], v[92:93]
	global_store_dwordx4 v[100:101], v[88:91], off offset:64
	global_load_dwordx4 v[88:91], v[102:103], off offset:512
	s_waitcnt vmcnt(0)
	v_pk_fma_f32 v[86:87], v[86:87], v[134:135], v[90:91]
	v_pk_fma_f32 v[84:85], v[84:85], v[132:133], v[88:89]
	global_store_dwordx4 v[100:101], v[84:87], off offset:512
	global_load_dwordx4 v[84:87], v[102:103], off offset:576
	s_waitcnt vmcnt(0)
	v_pk_fma_f32 v[82:83], v[82:83], v[130:131], v[86:87]
	v_pk_fma_f32 v[80:81], v[80:81], v[128:129], v[84:85]
	global_store_dwordx4 v[100:101], v[80:83], off offset:576
	s_nop 1
	v_or_b32_e32 v80, 48, v154
	v_ashrrev_i32_e32 v81, 31, v80
	v_lshlrev_b64 v[80:81], 11, v[80:81]
	v_lshl_add_u64 v[80:81], v[80:81], 0, v[152:153]
	v_lshlrev_b64 v[80:81], 2, v[80:81]
	v_lshl_add_u64 v[86:87], s[12:13], 0, v[80:81]
	v_lshl_add_u64 v[84:85], s[82:83], 0, v[80:81]
	global_load_dwordx4 v[80:83], v[86:87], off
	s_waitcnt vmcnt(0)
	v_pk_fma_f32 v[78:79], v[78:79], v[142:143], v[82:83]
	v_pk_fma_f32 v[76:77], v[76:77], v[140:141], v[80:81]
	global_store_dwordx4 v[84:85], v[76:79], off
	global_load_dwordx4 v[76:79], v[86:87], off offset:64
	s_waitcnt vmcnt(0)
	v_pk_fma_f32 v[74:75], v[74:75], v[138:139], v[78:79]
	v_pk_fma_f32 v[72:73], v[72:73], v[136:137], v[76:77]
	global_store_dwordx4 v[84:85], v[72:75], off offset:64
	global_load_dwordx4 v[72:75], v[86:87], off offset:512
	s_waitcnt vmcnt(0)
	v_pk_fma_f32 v[70:71], v[70:71], v[134:135], v[74:75]
	v_pk_fma_f32 v[68:69], v[68:69], v[132:133], v[72:73]
	global_store_dwordx4 v[84:85], v[68:71], off offset:512
	global_load_dwordx4 v[68:71], v[86:87], off offset:576
	s_waitcnt vmcnt(0)
	v_pk_fma_f32 v[66:67], v[66:67], v[130:131], v[70:71]
	v_pk_fma_f32 v[64:65], v[64:65], v[128:129], v[68:69]
	global_store_dwordx4 v[84:85], v[64:67], off offset:576
	s_nop 1
	v_lshl_add_u64 v[64:65], v[150:151], 0, s[14:15]
	v_lshl_add_u64 v[70:71], s[12:13], 0, v[64:65]
	v_lshl_add_u64 v[68:69], s[82:83], 0, v[64:65]
	global_load_dwordx4 v[64:67], v[70:71], off
	s_mov_b64 s[14:15], 0x120000
	s_waitcnt vmcnt(0)
	v_pk_fma_f32 v[62:63], v[62:63], v[142:143], v[66:67]
	v_pk_fma_f32 v[60:61], v[60:61], v[140:141], v[64:65]
	global_store_dwordx4 v[68:69], v[60:63], off
	global_load_dwordx4 v[60:63], v[70:71], off offset:64
	s_waitcnt vmcnt(0)
	v_pk_fma_f32 v[58:59], v[58:59], v[138:139], v[62:63]
	v_pk_fma_f32 v[56:57], v[56:57], v[136:137], v[60:61]
	global_store_dwordx4 v[68:69], v[56:59], off offset:64
	global_load_dwordx4 v[56:59], v[70:71], off offset:512
	s_waitcnt vmcnt(0)
	v_pk_fma_f32 v[54:55], v[54:55], v[134:135], v[58:59]
	v_pk_fma_f32 v[52:53], v[52:53], v[132:133], v[56:57]
	global_store_dwordx4 v[68:69], v[52:55], off offset:512
	global_load_dwordx4 v[52:55], v[70:71], off offset:576
	s_waitcnt vmcnt(0)
	v_pk_fma_f32 v[50:51], v[50:51], v[130:131], v[54:55]
	v_pk_fma_f32 v[48:49], v[48:49], v[128:129], v[52:53]
	global_store_dwordx4 v[68:69], v[48:51], off offset:576
	s_nop 1
	v_lshl_add_u64 v[48:49], v[150:151], 0, s[14:15]
	v_lshl_add_u64 v[54:55], s[12:13], 0, v[48:49]
	v_lshl_add_u64 v[52:53], s[82:83], 0, v[48:49]
	global_load_dwordx4 v[48:51], v[54:55], off
	s_mov_b64 s[14:15], 0x140000
	s_waitcnt vmcnt(0)
	v_pk_fma_f32 v[46:47], v[46:47], v[142:143], v[50:51]
	v_pk_fma_f32 v[44:45], v[44:45], v[140:141], v[48:49]
	global_store_dwordx4 v[52:53], v[44:47], off
	global_load_dwordx4 v[44:47], v[54:55], off offset:64
	s_waitcnt vmcnt(0)
	v_pk_fma_f32 v[42:43], v[42:43], v[138:139], v[46:47]
	v_pk_fma_f32 v[40:41], v[40:41], v[136:137], v[44:45]
	global_store_dwordx4 v[52:53], v[40:43], off offset:64
	global_load_dwordx4 v[40:43], v[54:55], off offset:512
	s_waitcnt vmcnt(0)
	v_pk_fma_f32 v[38:39], v[38:39], v[134:135], v[42:43]
	v_pk_fma_f32 v[36:37], v[36:37], v[132:133], v[40:41]
	global_store_dwordx4 v[52:53], v[36:39], off offset:512
	global_load_dwordx4 v[36:39], v[54:55], off offset:576
	s_waitcnt vmcnt(0)
	v_pk_fma_f32 v[34:35], v[34:35], v[130:131], v[38:39]
	v_pk_fma_f32 v[32:33], v[32:33], v[128:129], v[36:37]
	global_store_dwordx4 v[52:53], v[32:35], off offset:576
	s_nop 1
	v_lshl_add_u64 v[32:33], v[150:151], 0, s[14:15]
	v_lshl_add_u64 v[38:39], s[12:13], 0, v[32:33]
	v_lshl_add_u64 v[36:37], s[82:83], 0, v[32:33]
	global_load_dwordx4 v[32:35], v[38:39], off
	s_mov_b64 s[14:15], 0x160000
	s_waitcnt vmcnt(0)
	v_pk_fma_f32 v[30:31], v[30:31], v[142:143], v[34:35]
	v_pk_fma_f32 v[28:29], v[28:29], v[140:141], v[32:33]
	global_store_dwordx4 v[36:37], v[28:31], off
	global_load_dwordx4 v[28:31], v[38:39], off offset:64
	s_waitcnt vmcnt(0)
	v_pk_fma_f32 v[26:27], v[26:27], v[138:139], v[30:31]
	v_pk_fma_f32 v[24:25], v[24:25], v[136:137], v[28:29]
	global_store_dwordx4 v[36:37], v[24:27], off offset:64
	global_load_dwordx4 v[24:27], v[38:39], off offset:512
	s_waitcnt vmcnt(0)
	v_pk_fma_f32 v[22:23], v[22:23], v[134:135], v[26:27]
	v_pk_fma_f32 v[20:21], v[20:21], v[132:133], v[24:25]
	global_store_dwordx4 v[36:37], v[20:23], off offset:512
	global_load_dwordx4 v[20:23], v[38:39], off offset:576
	s_waitcnt vmcnt(0)
	v_pk_fma_f32 v[18:19], v[18:19], v[130:131], v[22:23]
	v_pk_fma_f32 v[16:17], v[16:17], v[128:129], v[20:21]
	global_store_dwordx4 v[36:37], v[16:19], off offset:576
	s_nop 1
	v_lshl_add_u64 v[16:17], v[150:151], 0, s[14:15]
	v_lshl_add_u64 v[22:23], s[12:13], 0, v[16:17]
	v_lshl_add_u64 v[20:21], s[82:83], 0, v[16:17]
	global_load_dwordx4 v[16:19], v[22:23], off
	s_waitcnt vmcnt(0)
	v_pk_fma_f32 v[14:15], v[14:15], v[142:143], v[18:19]
	v_pk_fma_f32 v[12:13], v[12:13], v[140:141], v[16:17]
	global_store_dwordx4 v[20:21], v[12:15], off
	global_load_dwordx4 v[12:15], v[22:23], off offset:64
	s_waitcnt vmcnt(0)
	v_pk_fma_f32 v[10:11], v[10:11], v[138:139], v[14:15]
	v_pk_fma_f32 v[8:9], v[8:9], v[136:137], v[12:13]
	global_store_dwordx4 v[20:21], v[8:11], off offset:64
	global_load_dwordx4 v[8:11], v[22:23], off offset:512
	s_waitcnt vmcnt(0)
	v_pk_fma_f32 v[6:7], v[6:7], v[134:135], v[10:11]
	v_pk_fma_f32 v[4:5], v[4:5], v[132:133], v[8:9]
	global_store_dwordx4 v[20:21], v[4:7], off offset:512
	global_load_dwordx4 v[4:7], v[22:23], off offset:576
	s_waitcnt vmcnt(0)
	v_pk_fma_f32 v[2:3], v[2:3], v[130:131], v[6:7]
	v_pk_fma_f32 v[0:1], v[0:1], v[128:129], v[4:5]
	global_store_dwordx4 v[20:21], v[0:3], off offset:576
	s_cbranch_vccz .LBB0_1074
	s_waitcnt vmcnt(0)
	s_mov_b32 s4, s86
	s_cmp_gt_u32 s4, 3
	s_mov_b32 s34, 0x10000
	s_movk_i32 s57, 0x404
	s_cbranch_scc1 .LBB0_1081
	s_barrier

.LBB0_1198:
	s_add_u32 s70, s8, 0xfff80080
	s_addc_u32 s71, s9, -1
	s_add_i32 s77, 0, 0x10000
	v_add_u32_e32 v140, s77, v225
	ds_read_b128 v[128:131], v140
	ds_read_b128 v[132:135], v140 offset:1024
	ds_read_b128 v[136:139], v140 offset:2048
	ds_read_b128 v[140:143], v140 offset:3072
	s_cmp_eq_u32 s76, 28
	s_cselect_b32 s73, s5, s71
	s_cselect_b32 s72, s4, s70
	s_cselect_b32 s71, s7, s75
	s_cselect_b32 s70, s6, s35
	s_add_i32 m0, s84, 0xc000
	ds_read_b128 v[144:147], v226
	ds_read_b128 v[148:151], v226 offset:1024
	ds_read_b128 v[152:155], v226 offset:2048
	ds_read_b128 v[156:159], v226 offset:3072
	ds_read_b128 v[160:163], v226 offset:4096
	ds_read_b128 v[164:167], v226 offset:5120
	ds_read_b128 v[168:171], v226 offset:6144
	ds_read_b128 v[172:175], v226 offset:7168
	global_load_lds_dwordx4 v190, s[8:9]
	s_add_i32 m0, s84, 0xe000
	s_nop 0
	global_load_lds_dwordx4 v188, s[8:9]
	s_waitcnt lgkmcnt(8)
	s_barrier
	s_waitcnt lgkmcnt(0)
	s_setprio 1
	s_waitcnt lgkmcnt(0)
	v_mfma_f32_16x16x32_bf16 v[124:127], v[128:131], v[144:147], v[124:127]
	v_mfma_f32_16x16x32_bf16 v[60:63], v[136:139], v[144:147], v[60:63]
	v_mfma_f32_16x16x32_bf16 v[116:119], v[128:131], v[152:155], v[116:119]
	v_mfma_f32_16x16x32_bf16 v[52:55], v[136:139], v[152:155], v[52:55]
	v_mfma_f32_16x16x32_bf16 v[108:111], v[128:131], v[160:163], v[108:111]
	v_mfma_f32_16x16x32_bf16 v[44:47], v[136:139], v[160:163], v[44:47]
	v_mfma_f32_16x16x32_bf16 v[100:103], v[128:131], v[168:171], v[100:103]
	v_mfma_f32_16x16x32_bf16 v[36:39], v[136:139], v[168:171], v[36:39]
	v_mfma_f32_16x16x32_bf16 v[124:127], v[132:135], v[148:151], v[124:127]
	v_mfma_f32_16x16x32_bf16 v[60:63], v[140:143], v[148:151], v[60:63]
	v_mfma_f32_16x16x32_bf16 v[116:119], v[132:135], v[156:159], v[116:119]
	v_mfma_f32_16x16x32_bf16 v[52:55], v[140:143], v[156:159], v[52:55]
	v_mfma_f32_16x16x32_bf16 v[108:111], v[132:135], v[164:167], v[108:111]
	v_mfma_f32_16x16x32_bf16 v[44:47], v[140:143], v[164:167], v[44:47]
	v_mfma_f32_16x16x32_bf16 v[100:103], v[132:135], v[172:175], v[100:103]
	v_mfma_f32_16x16x32_bf16 v[36:39], v[140:143], v[172:175], v[36:39]
	s_setprio 0
	s_barrier
	s_add_i32 vcc_lo, 0, 0x14000
	v_add_u32_e32 v176, vcc_lo, v225
	s_add_i32 s77, s77, s24
	ds_read_b128 v[192:195], v176
	ds_read_b128 v[196:199], v176 offset:1024
	ds_read_b128 v[204:207], v176 offset:2048
	ds_read_b128 v[212:215], v176 offset:3072
	s_mov_b32 m0, s77
	global_load_lds_dwordx4 v182, s[70:71]
	s_add_i32 m0, s77, 0x2000
	s_nop 0
	global_load_lds_dwordx4 v186, s[70:71]
	s_barrier
	s_waitcnt lgkmcnt(0)
	s_setprio 1
	s_waitcnt lgkmcnt(0)
	v_mfma_f32_16x16x32_bf16 v[120:123], v[192:195], v[144:147], v[120:123]
	v_mfma_f32_16x16x32_bf16 v[56:59], v[204:207], v[144:147], v[56:59]
	v_mfma_f32_16x16x32_bf16 v[112:115], v[192:195], v[152:155], v[112:115]
	v_mfma_f32_16x16x32_bf16 v[48:51], v[204:207], v[152:155], v[48:51]
	v_mfma_f32_16x16x32_bf16 v[104:107], v[192:195], v[160:163], v[104:107]
	v_mfma_f32_16x16x32_bf16 v[40:43], v[204:207], v[160:163], v[40:43]
	v_mfma_f32_16x16x32_bf16 v[96:99], v[192:195], v[168:171], v[96:99]
	v_mfma_f32_16x16x32_bf16 v[32:35], v[204:207], v[168:171], v[32:35]
	v_mfma_f32_16x16x32_bf16 v[120:123], v[196:199], v[148:151], v[120:123]
	v_mfma_f32_16x16x32_bf16 v[56:59], v[212:215], v[148:151], v[56:59]
	v_mfma_f32_16x16x32_bf16 v[112:115], v[196:199], v[156:159], v[112:115]
	v_mfma_f32_16x16x32_bf16 v[48:51], v[212:215], v[156:159], v[48:51]
	v_mfma_f32_16x16x32_bf16 v[104:107], v[196:199], v[164:167], v[104:107]
	v_mfma_f32_16x16x32_bf16 v[40:43], v[212:215], v[164:167], v[40:43]
	v_mfma_f32_16x16x32_bf16 v[96:99], v[196:199], v[172:175], v[96:99]
	v_mfma_f32_16x16x32_bf16 v[32:35], v[212:215], v[172:175], v[32:35]
	s_setprio 0
	s_mov_b32 m0, s84
	s_mov_b64 s[100:101], s[72:73]
	s_barrier
	ds_read_b128 v[144:147], v226 offset:16384
	ds_read_b128 v[148:151], v226 offset:17408
	ds_read_b128 v[152:155], v226 offset:18432
	ds_read_b128 v[156:159], v226 offset:19456
	ds_read_b128 v[160:163], v226 offset:20480
	ds_read_b128 v[164:167], v226 offset:21504
	ds_read_b128 v[168:171], v226 offset:22528
	ds_read_b128 v[172:175], v226 offset:23552
	global_load_lds_dwordx4 v180, s[72:73]
	s_mov_b64 s[100:101], s[72:73]
	s_mov_b32 m0, s85
	s_nop 0
	global_load_lds_dwordx4 v184, s[72:73]
	s_barrier
	s_waitcnt lgkmcnt(0)
	s_setprio 1
	s_waitcnt lgkmcnt(0)
	v_mfma_f32_16x16x32_bf16 v[92:95], v[128:131], v[144:147], v[92:95]
	v_mfma_f32_16x16x32_bf16 v[28:31], v[136:139], v[144:147], v[28:31]
	v_mfma_f32_16x16x32_bf16 v[84:87], v[128:131], v[152:155], v[84:87]
	v_mfma_f32_16x16x32_bf16 v[20:23], v[136:139], v[152:155], v[20:23]
	v_mfma_f32_16x16x32_bf16 v[76:79], v[128:131], v[160:163], v[76:79]
	v_mfma_f32_16x16x32_bf16 v[12:15], v[136:139], v[160:163], v[12:15]
	v_mfma_f32_16x16x32_bf16 v[68:71], v[128:131], v[168:171], v[68:71]
	v_mfma_f32_16x16x32_bf16 v[4:7], v[136:139], v[168:171], v[4:7]
	v_mfma_f32_16x16x32_bf16 v[92:95], v[132:135], v[148:151], v[92:95]
	v_mfma_f32_16x16x32_bf16 v[28:31], v[140:143], v[148:151], v[28:31]
	v_mfma_f32_16x16x32_bf16 v[84:87], v[132:135], v[156:159], v[84:87]
	v_mfma_f32_16x16x32_bf16 v[20:23], v[140:143], v[156:159], v[20:23]
	v_mfma_f32_16x16x32_bf16 v[76:79], v[132:135], v[164:167], v[76:79]
	v_mfma_f32_16x16x32_bf16 v[12:15], v[140:143], v[164:167], v[12:15]
	v_mfma_f32_16x16x32_bf16 v[68:71], v[132:135], v[172:175], v[68:71]
	v_mfma_f32_16x16x32_bf16 v[4:7], v[140:143], v[172:175], v[4:7]
	s_setprio 0
	s_barrier
	s_add_u32 s78, s70, 0x80000
	s_addc_u32 s79, s71, 0
	s_add_i32 s77, vcc_lo, s24
	s_mov_b32 m0, s77
	s_nop 0
	global_load_lds_dwordx4 v182, s[78:79]
	s_add_i32 m0, s77, 0x2000
	s_nop 0
	global_load_lds_dwordx4 v186, s[78:79]
	s_waitcnt vmcnt(6)
	s_barrier
	s_setprio 1
	v_mfma_f32_16x16x32_bf16 v[88:91], v[192:195], v[144:147], v[88:91]
	v_mfma_f32_16x16x32_bf16 v[24:27], v[204:207], v[144:147], v[24:27]
	v_mfma_f32_16x16x32_bf16 v[80:83], v[192:195], v[152:155], v[80:83]
	v_mfma_f32_16x16x32_bf16 v[16:19], v[204:207], v[152:155], v[16:19]
	v_mfma_f32_16x16x32_bf16 v[72:75], v[192:195], v[160:163], v[72:75]
	v_mfma_f32_16x16x32_bf16 v[8:11], v[204:207], v[160:163], v[8:11]
	v_mfma_f32_16x16x32_bf16 v[64:67], v[192:195], v[168:171], v[64:67]
	v_mfma_f32_16x16x32_bf16 v[0:3], v[204:207], v[168:171], v[0:3]
	v_mfma_f32_16x16x32_bf16 v[88:91], v[196:199], v[148:151], v[88:91]
	v_mfma_f32_16x16x32_bf16 v[24:27], v[212:215], v[148:151], v[24:27]
	v_mfma_f32_16x16x32_bf16 v[80:83], v[196:199], v[156:159], v[80:83]
	v_mfma_f32_16x16x32_bf16 v[16:19], v[212:215], v[156:159], v[16:19]
	v_mfma_f32_16x16x32_bf16 v[72:75], v[196:199], v[164:167], v[72:75]
	v_mfma_f32_16x16x32_bf16 v[8:11], v[212:215], v[164:167], v[8:11]
	v_mfma_f32_16x16x32_bf16 v[64:67], v[196:199], v[172:175], v[64:67]
	v_mfma_f32_16x16x32_bf16 v[0:3], v[212:215], v[172:175], v[0:3]
	s_setprio 0
	s_add_i32 s77, 0, 0x18000
	v_add_u32_e32 v140, s77, v225
	s_barrier
	ds_read_b128 v[128:131], v140
	ds_read_b128 v[132:135], v140 offset:1024
	ds_read_b128 v[136:139], v140 offset:2048
	ds_read_b128 v[140:143], v140 offset:3072
	s_add_u32 s72, s72, 0x80000
	s_addc_u32 s73, s73, 0
	s_mov_b32 m0, s86
	ds_read_b128 v[144:147], v226 offset:32768
	ds_read_b128 v[148:151], v226 offset:33792
	ds_read_b128 v[152:155], v226 offset:34816
	ds_read_b128 v[156:159], v226 offset:35840
	ds_read_b128 v[160:163], v226 offset:36864
	ds_read_b128 v[164:167], v226 offset:37888
	ds_read_b128 v[168:171], v226 offset:38912
	ds_read_b128 v[172:175], v226 offset:39936
	global_load_lds_dwordx4 v180, s[72:73]
	s_mov_b32 m0, s87
	s_nop 0
	global_load_lds_dwordx4 v184, s[72:73]
	s_waitcnt lgkmcnt(8)
	s_barrier
	s_waitcnt lgkmcnt(0)
	s_setprio 1
	s_waitcnt lgkmcnt(0)
	v_mfma_f32_16x16x32_bf16 v[124:127], v[128:131], v[144:147], v[124:127]
	v_mfma_f32_16x16x32_bf16 v[60:63], v[136:139], v[144:147], v[60:63]
	v_mfma_f32_16x16x32_bf16 v[116:119], v[128:131], v[152:155], v[116:119]
	v_mfma_f32_16x16x32_bf16 v[52:55], v[136:139], v[152:155], v[52:55]
	v_mfma_f32_16x16x32_bf16 v[108:111], v[128:131], v[160:163], v[108:111]
	v_mfma_f32_16x16x32_bf16 v[44:47], v[136:139], v[160:163], v[44:47]
	v_mfma_f32_16x16x32_bf16 v[100:103], v[128:131], v[168:171], v[100:103]
	v_mfma_f32_16x16x32_bf16 v[36:39], v[136:139], v[168:171], v[36:39]
	v_mfma_f32_16x16x32_bf16 v[124:127], v[132:135], v[148:151], v[124:127]
	v_mfma_f32_16x16x32_bf16 v[60:63], v[140:143], v[148:151], v[60:63]
	v_mfma_f32_16x16x32_bf16 v[116:119], v[132:135], v[156:159], v[116:119]
	v_mfma_f32_16x16x32_bf16 v[52:55], v[140:143], v[156:159], v[52:55]
	v_mfma_f32_16x16x32_bf16 v[108:111], v[132:135], v[164:167], v[108:111]
	v_mfma_f32_16x16x32_bf16 v[44:47], v[140:143], v[164:167], v[44:47]
	v_mfma_f32_16x16x32_bf16 v[100:103], v[132:135], v[172:175], v[100:103]
	v_mfma_f32_16x16x32_bf16 v[36:39], v[140:143], v[172:175], v[36:39]
	s_setprio 0
	s_barrier
	s_add_i32 s72, 0, 0x1c000
	s_add_i32 s73, s77, s24
	v_add_u32_e32 v178, s72, v225
	s_add_i32 m0, s73, 0xffffff80
	ds_read_b128 v[192:195], v178
	ds_read_b128 v[196:199], v178 offset:1024
	ds_read_b128 v[204:207], v178 offset:2048
	ds_read_b128 v[212:215], v178 offset:3072
	global_load_lds_dwordx4 v182, s[70:71] offset:128
	s_add_i32 m0, s73, 0x1f80
	s_nop 0
	global_load_lds_dwordx4 v186, s[70:71] offset:128
	s_barrier
	s_waitcnt lgkmcnt(0)
	s_setprio 1
	s_waitcnt lgkmcnt(0)
	v_mfma_f32_16x16x32_bf16 v[120:123], v[192:195], v[144:147], v[120:123]
	v_mfma_f32_16x16x32_bf16 v[56:59], v[204:207], v[144:147], v[56:59]
	v_mfma_f32_16x16x32_bf16 v[112:115], v[192:195], v[152:155], v[112:115]
	v_mfma_f32_16x16x32_bf16 v[48:51], v[204:207], v[152:155], v[48:51]
	v_mfma_f32_16x16x32_bf16 v[104:107], v[192:195], v[160:163], v[104:107]
	v_mfma_f32_16x16x32_bf16 v[40:43], v[204:207], v[160:163], v[40:43]
	v_mfma_f32_16x16x32_bf16 v[96:99], v[192:195], v[168:171], v[96:99]
	v_mfma_f32_16x16x32_bf16 v[32:35], v[204:207], v[168:171], v[32:35]
	v_mfma_f32_16x16x32_bf16 v[120:123], v[196:199], v[148:151], v[120:123]
	v_mfma_f32_16x16x32_bf16 v[56:59], v[212:215], v[148:151], v[56:59]
	v_mfma_f32_16x16x32_bf16 v[112:115], v[196:199], v[156:159], v[112:115]
	v_mfma_f32_16x16x32_bf16 v[48:51], v[212:215], v[156:159], v[48:51]
	v_mfma_f32_16x16x32_bf16 v[104:107], v[196:199], v[164:167], v[104:107]
	v_mfma_f32_16x16x32_bf16 v[40:43], v[212:215], v[164:167], v[40:43]
	v_mfma_f32_16x16x32_bf16 v[96:99], v[196:199], v[172:175], v[96:99]
	v_mfma_f32_16x16x32_bf16 v[32:35], v[212:215], v[172:175], v[32:35]
	s_setprio 0
	s_add_i32 m0, s59, 0xffffff80
	s_barrier
	ds_read_b128 v[144:147], v226 offset:49152
	ds_read_b128 v[148:151], v226 offset:50176
	ds_read_b128 v[152:155], v226 offset:51200
	ds_read_b128 v[156:159], v226 offset:52224
	ds_read_b128 v[160:163], v226 offset:53248
	ds_read_b128 v[164:167], v226 offset:54272
	ds_read_b128 v[168:171], v226 offset:55296
	ds_read_b128 v[172:175], v226 offset:56320
	global_load_lds_dwordx4 v180, s[100:101] offset:128
	s_add_i32 m0, s20, 0xffffff80
	s_nop 0
	global_load_lds_dwordx4 v184, s[100:101] offset:128
	s_barrier
	s_waitcnt lgkmcnt(0)
	s_setprio 1
	s_waitcnt lgkmcnt(0)
	v_mfma_f32_16x16x32_bf16 v[92:95], v[128:131], v[144:147], v[92:95]
	v_mfma_f32_16x16x32_bf16 v[28:31], v[136:139], v[144:147], v[28:31]
	v_mfma_f32_16x16x32_bf16 v[84:87], v[128:131], v[152:155], v[84:87]
	v_mfma_f32_16x16x32_bf16 v[20:23], v[136:139], v[152:155], v[20:23]
	v_mfma_f32_16x16x32_bf16 v[76:79], v[128:131], v[160:163], v[76:79]
	v_mfma_f32_16x16x32_bf16 v[12:15], v[136:139], v[160:163], v[12:15]
	v_mfma_f32_16x16x32_bf16 v[68:71], v[128:131], v[168:171], v[68:71]
	v_mfma_f32_16x16x32_bf16 v[4:7], v[136:139], v[168:171], v[4:7]
	v_mfma_f32_16x16x32_bf16 v[92:95], v[132:135], v[148:151], v[92:95]
	v_mfma_f32_16x16x32_bf16 v[28:31], v[140:143], v[148:151], v[28:31]
	v_mfma_f32_16x16x32_bf16 v[84:87], v[132:135], v[156:159], v[84:87]
	v_mfma_f32_16x16x32_bf16 v[20:23], v[140:143], v[156:159], v[20:23]
	v_mfma_f32_16x16x32_bf16 v[76:79], v[132:135], v[164:167], v[76:79]
	v_mfma_f32_16x16x32_bf16 v[12:15], v[140:143], v[164:167], v[12:15]
	v_mfma_f32_16x16x32_bf16 v[68:71], v[132:135], v[172:175], v[68:71]
	v_mfma_f32_16x16x32_bf16 v[4:7], v[140:143], v[172:175], v[4:7]
	s_setprio 0
	s_barrier
	s_add_u32 s70, s70, 0x80080
	s_addc_u32 s71, s71, 0
	s_add_i32 s72, s72, s24
	s_mov_b32 m0, s72
	s_nop 0
	global_load_lds_dwordx4 v182, s[70:71]
	s_add_i32 m0, s72, 0x2000
	s_nop 0
	global_load_lds_dwordx4 v186, s[70:71]
	s_waitcnt vmcnt(6)
	s_barrier
	s_setprio 1
	v_mfma_f32_16x16x32_bf16 v[88:91], v[192:195], v[144:147], v[88:91]
	v_mfma_f32_16x16x32_bf16 v[24:27], v[204:207], v[144:147], v[24:27]
	v_mfma_f32_16x16x32_bf16 v[80:83], v[192:195], v[152:155], v[80:83]
	v_mfma_f32_16x16x32_bf16 v[16:19], v[204:207], v[152:155], v[16:19]
	v_mfma_f32_16x16x32_bf16 v[72:75], v[192:195], v[160:163], v[72:75]
	v_mfma_f32_16x16x32_bf16 v[8:11], v[204:207], v[160:163], v[8:11]
	v_mfma_f32_16x16x32_bf16 v[64:67], v[192:195], v[168:171], v[64:67]
	v_mfma_f32_16x16x32_bf16 v[0:3], v[204:207], v[168:171], v[0:3]
	v_mfma_f32_16x16x32_bf16 v[88:91], v[196:199], v[148:151], v[88:91]
	v_mfma_f32_16x16x32_bf16 v[24:27], v[212:215], v[148:151], v[24:27]
	v_mfma_f32_16x16x32_bf16 v[80:83], v[196:199], v[156:159], v[80:83]
	v_mfma_f32_16x16x32_bf16 v[16:19], v[212:215], v[156:159], v[16:19]
	v_mfma_f32_16x16x32_bf16 v[72:75], v[196:199], v[164:167], v[72:75]
	v_mfma_f32_16x16x32_bf16 v[8:11], v[212:215], v[164:167], v[8:11]
	v_mfma_f32_16x16x32_bf16 v[64:67], v[196:199], v[172:175], v[64:67]
	v_mfma_f32_16x16x32_bf16 v[0:3], v[212:215], v[172:175], v[0:3]
	s_setprio 0
	s_add_i32 s76, s76, 2
	s_add_u32 s35, s35, 0x100
	s_addc_u32 s75, s75, 0
	s_add_u32 s8, s8, 0x100
	s_addc_u32 s9, s9, 0
	s_cmp_gt_u32 s76, 29
	s_barrier
	s_cbranch_scc0 .LBB0_1198
	v_mov_b32_e32 v140, v224
	v_mov_b32_e32 v194, v223
	v_readlane_b32 s4, v255, 16
	v_lshlrev_b32_e32 v227, 6, v140
	v_cmp_lt_i32_e32 vcc, 14, v194
	v_add_u32_e32 v141, s4, v227
	s_mov_b64 s[4:5], 0
	s_and_saveexec_b64 s[6:7], vcc
	s_xor_b64 s[6:7], exec, s[6:7]
	s_cbranch_execz .LBB0_1203
	v_cmp_eq_u32_e32 vcc, 15, v194
	s_and_saveexec_b64 s[8:9], vcc
	s_mov_b64 s[4:5], exec
	ds_write_b128 v141, v[100:103] offset:256
	s_or_b64 exec, exec, s[8:9]
	s_and_b64 s[4:5], s[4:5], exec

.LBB0_1363:
	s_add_u32 s16, s14, 0x100
	s_addc_u32 s17, s15, 0
	s_add_i32 s68, 0, 0x10000
	v_add_u32_e32 v76, s68, v153
	ds_read_b128 v[48:51], v76
	ds_read_b128 v[68:71], v76 offset:1024
	ds_read_b128 v[72:75], v76 offset:2048
	ds_read_b128 v[76:79], v76 offset:3072
	s_cmpk_eq_i32 s67, 0x52
	s_cselect_b32 s21, s11, s17
	s_cselect_b32 s20, s10, s16
	s_cselect_b32 s19, s13, s66
	s_cselect_b32 s18, s12, s63
	v_lshl_add_u64 v[150:151], s[14:15], 0, v[148:149]
	s_add_i32 m0, s29, 0xc000
	ds_read_b128 v[156:159], v155
	ds_read_b128 v[160:163], v155 offset:1024
	ds_read_b128 v[164:167], v155 offset:2048
	ds_read_b128 v[168:171], v155 offset:3072
	ds_read_b128 v[172:175], v155 offset:4096
	ds_read_b128 v[180:183], v155 offset:5120
	ds_read_b128 v[184:187], v155 offset:6144
	ds_read_b128 v[188:191], v155 offset:7168
	global_load_lds_dwordx4 v[150:151], off
	v_lshl_add_u64 v[150:151], s[14:15], 0, v[146:147]
	s_add_i32 m0, s29, 0xe000
	s_nop 0
	global_load_lds_dwordx4 v[150:151], off
	s_waitcnt lgkmcnt(8)
	s_barrier
	s_waitcnt lgkmcnt(0)
	s_setprio 1
	s_waitcnt lgkmcnt(0)
	v_mfma_f32_16x16x32_bf16 v[140:143], v[48:51], v[156:159], v[140:143]
	v_mfma_f32_16x16x32_bf16 v[136:139], v[72:75], v[156:159], v[136:139]
	v_mfma_f32_16x16x32_bf16 v[124:127], v[48:51], v[164:167], v[124:127]
	v_mfma_f32_16x16x32_bf16 v[120:123], v[72:75], v[164:167], v[120:123]
	v_mfma_f32_16x16x32_bf16 v[116:119], v[48:51], v[172:175], v[116:119]
	v_mfma_f32_16x16x32_bf16 v[112:115], v[72:75], v[172:175], v[112:115]
	v_mfma_f32_16x16x32_bf16 v[100:103], v[48:51], v[184:187], v[100:103]
	v_mfma_f32_16x16x32_bf16 v[96:99], v[72:75], v[184:187], v[96:99]
	v_mfma_f32_16x16x32_bf16 v[140:143], v[68:71], v[160:163], v[140:143]
	v_mfma_f32_16x16x32_bf16 v[136:139], v[76:79], v[160:163], v[136:139]
	v_mfma_f32_16x16x32_bf16 v[124:127], v[68:71], v[168:171], v[124:127]
	v_mfma_f32_16x16x32_bf16 v[120:123], v[76:79], v[168:171], v[120:123]
	v_mfma_f32_16x16x32_bf16 v[116:119], v[68:71], v[180:183], v[116:119]
	v_mfma_f32_16x16x32_bf16 v[112:115], v[76:79], v[180:183], v[112:115]
	v_mfma_f32_16x16x32_bf16 v[100:103], v[68:71], v[188:191], v[100:103]
	v_mfma_f32_16x16x32_bf16 v[96:99], v[76:79], v[188:191], v[96:99]
	s_setprio 0
	s_barrier
	s_add_i32 s69, 0, 0x14000
	v_add_u32_e32 v150, s69, v153
	s_add_i32 s14, s68, s28
	ds_read_b128 v[192:195], v150
	ds_read_b128 v[196:199], v150 offset:1024
	ds_read_b128 v[204:207], v150 offset:2048
	ds_read_b128 v[212:215], v150 offset:3072
	s_mov_b32 m0, s14
	global_load_lds_dwordx4 v178, s[18:19]
	s_add_i32 m0, s14, 0x2000
	s_nop 0
	global_load_lds_dwordx4 v144, s[18:19]
	s_barrier
	s_waitcnt lgkmcnt(0)
	s_setprio 1
	s_waitcnt lgkmcnt(0)
	v_mfma_f32_16x16x32_bf16 v[132:135], v[192:195], v[156:159], v[132:135]
	v_mfma_f32_16x16x32_bf16 v[128:131], v[204:207], v[156:159], v[128:131]
	v_mfma_f32_16x16x32_bf16 v[108:111], v[192:195], v[164:167], v[108:111]
	v_mfma_f32_16x16x32_bf16 v[104:107], v[204:207], v[164:167], v[104:107]
	v_mfma_f32_16x16x32_bf16 v[92:95], v[192:195], v[172:175], v[92:95]
	v_mfma_f32_16x16x32_bf16 v[88:91], v[204:207], v[172:175], v[88:91]
	v_mfma_f32_16x16x32_bf16 v[84:87], v[192:195], v[184:187], v[84:87]
	v_mfma_f32_16x16x32_bf16 v[80:83], v[204:207], v[184:187], v[80:83]
	v_mfma_f32_16x16x32_bf16 v[132:135], v[196:199], v[160:163], v[132:135]
	v_mfma_f32_16x16x32_bf16 v[128:131], v[212:215], v[160:163], v[128:131]
	v_mfma_f32_16x16x32_bf16 v[108:111], v[196:199], v[168:171], v[108:111]
	v_mfma_f32_16x16x32_bf16 v[104:107], v[212:215], v[168:171], v[104:107]
	v_mfma_f32_16x16x32_bf16 v[92:95], v[196:199], v[180:183], v[92:95]
	v_mfma_f32_16x16x32_bf16 v[88:91], v[212:215], v[180:183], v[88:91]
	v_mfma_f32_16x16x32_bf16 v[84:87], v[196:199], v[188:191], v[84:87]
	v_mfma_f32_16x16x32_bf16 v[80:83], v[212:215], v[188:191], v[80:83]
	s_setprio 0
	s_mov_b32 m0, s29
	s_mov_b64 s[100:101], s[20:21]
	s_barrier
	ds_read_b128 v[156:159], v155 offset:16384
	ds_read_b128 v[160:163], v155 offset:17408
	ds_read_b128 v[164:167], v155 offset:18432
	ds_read_b128 v[168:171], v155 offset:19456
	ds_read_b128 v[172:175], v155 offset:20480
	ds_read_b128 v[180:183], v155 offset:21504
	ds_read_b128 v[184:187], v155 offset:22528
	ds_read_b128 v[188:191], v155 offset:23552
	global_load_lds_dwordx4 v178, s[20:21]
	s_mov_b64 s[100:101], s[20:21]
	s_mov_b32 m0, s30
	s_nop 0
	global_load_lds_dwordx4 v144, s[20:21]
	s_barrier
	s_waitcnt lgkmcnt(0)
	s_setprio 1
	s_waitcnt lgkmcnt(0)
	v_mfma_f32_16x16x32_bf16 v[64:67], v[48:51], v[156:159], v[64:67]
	v_mfma_f32_16x16x32_bf16 v[60:63], v[72:75], v[156:159], v[60:63]
	v_mfma_f32_16x16x32_bf16 v[44:47], v[48:51], v[164:167], v[44:47]
	v_mfma_f32_16x16x32_bf16 v[40:43], v[72:75], v[164:167], v[40:43]
	v_mfma_f32_16x16x32_bf16 v[28:31], v[48:51], v[172:175], v[28:31]
	v_mfma_f32_16x16x32_bf16 v[24:27], v[72:75], v[172:175], v[24:27]
	v_mfma_f32_16x16x32_bf16 v[12:15], v[48:51], v[184:187], v[12:15]
	v_mfma_f32_16x16x32_bf16 v[8:11], v[72:75], v[184:187], v[8:11]
	v_mfma_f32_16x16x32_bf16 v[64:67], v[68:71], v[160:163], v[64:67]
	v_mfma_f32_16x16x32_bf16 v[60:63], v[76:79], v[160:163], v[60:63]
	v_mfma_f32_16x16x32_bf16 v[44:47], v[68:71], v[168:171], v[44:47]
	v_mfma_f32_16x16x32_bf16 v[40:43], v[76:79], v[168:171], v[40:43]
	v_mfma_f32_16x16x32_bf16 v[28:31], v[68:71], v[180:183], v[28:31]
	v_mfma_f32_16x16x32_bf16 v[24:27], v[76:79], v[180:183], v[24:27]
	v_mfma_f32_16x16x32_bf16 v[12:15], v[68:71], v[188:191], v[12:15]
	v_mfma_f32_16x16x32_bf16 v[8:11], v[76:79], v[188:191], v[8:11]
	s_setprio 0
	s_barrier
	s_add_u32 s14, s18, 0x158000
	s_addc_u32 s15, s19, 0
	s_add_i32 s68, s69, s28
	s_mov_b32 m0, s68
	s_nop 0
	global_load_lds_dwordx4 v178, s[14:15]
	s_add_i32 m0, s68, 0x2000
	s_nop 0
	global_load_lds_dwordx4 v144, s[14:15]
	s_waitcnt vmcnt(6)
	s_barrier
	s_setprio 1
	v_mfma_f32_16x16x32_bf16 v[52:55], v[204:207], v[156:159], v[52:55]
	v_mfma_f32_16x16x32_bf16 v[36:39], v[192:195], v[164:167], v[36:39]
	v_mfma_f32_16x16x32_bf16 v[32:35], v[204:207], v[164:167], v[32:35]
	v_mfma_f32_16x16x32_bf16 v[20:23], v[192:195], v[172:175], v[20:23]
	v_mfma_f32_16x16x32_bf16 v[16:19], v[204:207], v[172:175], v[16:19]
	v_mfma_f32_16x16x32_bf16 v[4:7], v[192:195], v[184:187], v[4:7]
	v_mfma_f32_16x16x32_bf16 v[0:3], v[204:207], v[184:187], v[0:3]
	v_mfma_f32_16x16x32_bf16 v[48:51], v[192:195], v[156:159], v[56:59]
	v_mfma_f32_16x16x32_bf16 v[52:55], v[212:215], v[160:163], v[52:55]
	v_mfma_f32_16x16x32_bf16 v[36:39], v[196:199], v[168:171], v[36:39]
	v_mfma_f32_16x16x32_bf16 v[32:35], v[212:215], v[168:171], v[32:35]
	v_mfma_f32_16x16x32_bf16 v[20:23], v[196:199], v[180:183], v[20:23]
	v_mfma_f32_16x16x32_bf16 v[16:19], v[212:215], v[180:183], v[16:19]
	v_mfma_f32_16x16x32_bf16 v[4:7], v[196:199], v[188:191], v[4:7]
	v_mfma_f32_16x16x32_bf16 v[0:3], v[212:215], v[188:191], v[0:3]
	v_mfma_f32_16x16x32_bf16 v[48:51], v[196:199], v[160:163], v[48:51]
	s_setprio 0
	s_add_i32 s68, 0, 0x18000
	v_add_u32_e32 v76, s68, v153
	s_barrier
	ds_read_b128 v[56:59], v76
	ds_read_b128 v[68:71], v76 offset:1024
	ds_read_b128 v[72:75], v76 offset:2048
	ds_read_b128 v[76:79], v76 offset:3072
	s_add_u32 s14, s20, 0x158000
	s_addc_u32 s15, s21, 0
	s_mov_b32 m0, s31
	ds_read_b128 v[156:159], v155 offset:32768
	ds_read_b128 v[160:163], v155 offset:33792
	ds_read_b128 v[164:167], v155 offset:34816
	ds_read_b128 v[168:171], v155 offset:35840
	ds_read_b128 v[172:175], v155 offset:36864
	ds_read_b128 v[180:183], v155 offset:37888
	ds_read_b128 v[184:187], v155 offset:38912
	ds_read_b128 v[188:191], v155 offset:39936
	global_load_lds_dwordx4 v178, s[14:15]
	s_mov_b32 m0, s34
	s_nop 0
	global_load_lds_dwordx4 v144, s[14:15]
	s_waitcnt lgkmcnt(8)
	s_barrier
	s_waitcnt lgkmcnt(0)
	s_setprio 1
	s_waitcnt lgkmcnt(0)
	v_mfma_f32_16x16x32_bf16 v[140:143], v[56:59], v[156:159], v[140:143]
	v_mfma_f32_16x16x32_bf16 v[136:139], v[72:75], v[156:159], v[136:139]
	v_mfma_f32_16x16x32_bf16 v[124:127], v[56:59], v[164:167], v[124:127]
	v_mfma_f32_16x16x32_bf16 v[120:123], v[72:75], v[164:167], v[120:123]
	v_mfma_f32_16x16x32_bf16 v[116:119], v[56:59], v[172:175], v[116:119]
	v_mfma_f32_16x16x32_bf16 v[112:115], v[72:75], v[172:175], v[112:115]
	v_mfma_f32_16x16x32_bf16 v[100:103], v[56:59], v[184:187], v[100:103]
	v_mfma_f32_16x16x32_bf16 v[96:99], v[72:75], v[184:187], v[96:99]
	v_mfma_f32_16x16x32_bf16 v[140:143], v[68:71], v[160:163], v[140:143]
	v_mfma_f32_16x16x32_bf16 v[136:139], v[76:79], v[160:163], v[136:139]
	v_mfma_f32_16x16x32_bf16 v[124:127], v[68:71], v[168:171], v[124:127]
	v_mfma_f32_16x16x32_bf16 v[120:123], v[76:79], v[168:171], v[120:123]
	v_mfma_f32_16x16x32_bf16 v[116:119], v[68:71], v[180:183], v[116:119]
	v_mfma_f32_16x16x32_bf16 v[112:115], v[76:79], v[180:183], v[112:115]
	v_mfma_f32_16x16x32_bf16 v[100:103], v[68:71], v[188:191], v[100:103]
	v_mfma_f32_16x16x32_bf16 v[96:99], v[76:79], v[188:191], v[96:99]
	s_setprio 0
	s_barrier
	s_add_i32 s20, 0, 0x1c000
	s_add_i32 s14, s68, s28
	v_add_u32_e32 v212, s20, v153
	s_add_i32 m0, s14, 0xffffff80
	ds_read_b128 v[192:195], v212
	ds_read_b128 v[196:199], v212 offset:1024
	ds_read_b128 v[204:207], v212 offset:2048
	ds_read_b128 v[212:215], v212 offset:3072
	global_load_lds_dwordx4 v178, s[18:19] offset:128
	s_add_i32 m0, s14, 0x1f80
	s_nop 0
	global_load_lds_dwordx4 v144, s[18:19] offset:128
	s_barrier
	s_waitcnt lgkmcnt(0)
	s_setprio 1
	s_waitcnt lgkmcnt(0)
	v_mfma_f32_16x16x32_bf16 v[132:135], v[192:195], v[156:159], v[132:135]
	v_mfma_f32_16x16x32_bf16 v[128:131], v[204:207], v[156:159], v[128:131]
	v_mfma_f32_16x16x32_bf16 v[108:111], v[192:195], v[164:167], v[108:111]
	v_mfma_f32_16x16x32_bf16 v[104:107], v[204:207], v[164:167], v[104:107]
	v_mfma_f32_16x16x32_bf16 v[92:95], v[192:195], v[172:175], v[92:95]
	v_mfma_f32_16x16x32_bf16 v[88:91], v[204:207], v[172:175], v[88:91]
	v_mfma_f32_16x16x32_bf16 v[84:87], v[192:195], v[184:187], v[84:87]
	v_mfma_f32_16x16x32_bf16 v[80:83], v[204:207], v[184:187], v[80:83]
	v_mfma_f32_16x16x32_bf16 v[132:135], v[196:199], v[160:163], v[132:135]
	v_mfma_f32_16x16x32_bf16 v[128:131], v[212:215], v[160:163], v[128:131]
	v_mfma_f32_16x16x32_bf16 v[108:111], v[196:199], v[168:171], v[108:111]
	v_mfma_f32_16x16x32_bf16 v[104:107], v[212:215], v[168:171], v[104:107]
	v_mfma_f32_16x16x32_bf16 v[92:95], v[196:199], v[180:183], v[92:95]
	v_mfma_f32_16x16x32_bf16 v[88:91], v[212:215], v[180:183], v[88:91]
	v_mfma_f32_16x16x32_bf16 v[84:87], v[196:199], v[188:191], v[84:87]
	v_mfma_f32_16x16x32_bf16 v[80:83], v[212:215], v[188:191], v[80:83]
	s_setprio 0
	s_add_i32 m0, s56, 0xffffff80
	s_barrier
	ds_read_b128 v[156:159], v155 offset:49152
	ds_read_b128 v[160:163], v155 offset:50176
	ds_read_b128 v[164:167], v155 offset:51200
	ds_read_b128 v[168:171], v155 offset:52224
	ds_read_b128 v[172:175], v155 offset:53248
	ds_read_b128 v[180:183], v155 offset:54272
	ds_read_b128 v[184:187], v155 offset:55296
	ds_read_b128 v[188:191], v155 offset:56320
	global_load_lds_dwordx4 v178, s[100:101] offset:128
	s_add_i32 m0, s57, 0xffffff80
	s_nop 0
	global_load_lds_dwordx4 v144, s[100:101] offset:128
	s_barrier
	s_waitcnt lgkmcnt(0)
	s_setprio 1
	s_waitcnt lgkmcnt(0)
	v_mfma_f32_16x16x32_bf16 v[64:67], v[56:59], v[156:159], v[64:67]
	v_mfma_f32_16x16x32_bf16 v[60:63], v[72:75], v[156:159], v[60:63]
	v_mfma_f32_16x16x32_bf16 v[44:47], v[56:59], v[164:167], v[44:47]
	v_mfma_f32_16x16x32_bf16 v[40:43], v[72:75], v[164:167], v[40:43]
	v_mfma_f32_16x16x32_bf16 v[28:31], v[56:59], v[172:175], v[28:31]
	v_mfma_f32_16x16x32_bf16 v[24:27], v[72:75], v[172:175], v[24:27]
	v_mfma_f32_16x16x32_bf16 v[12:15], v[56:59], v[184:187], v[12:15]
	v_mfma_f32_16x16x32_bf16 v[8:11], v[72:75], v[184:187], v[8:11]
	v_mfma_f32_16x16x32_bf16 v[64:67], v[68:71], v[160:163], v[64:67]
	v_mfma_f32_16x16x32_bf16 v[60:63], v[76:79], v[160:163], v[60:63]
	v_mfma_f32_16x16x32_bf16 v[44:47], v[68:71], v[168:171], v[44:47]
	v_mfma_f32_16x16x32_bf16 v[40:43], v[76:79], v[168:171], v[40:43]
	v_mfma_f32_16x16x32_bf16 v[28:31], v[68:71], v[180:183], v[28:31]
	v_mfma_f32_16x16x32_bf16 v[24:27], v[76:79], v[180:183], v[24:27]
	v_mfma_f32_16x16x32_bf16 v[12:15], v[68:71], v[188:191], v[12:15]
	v_mfma_f32_16x16x32_bf16 v[8:11], v[76:79], v[188:191], v[8:11]
	s_setprio 0
	s_barrier
	s_add_u32 s14, s18, 0x158080
	s_addc_u32 s15, s19, 0
	s_add_i32 s18, s20, s28
	s_mov_b32 m0, s18
	s_nop 0
	global_load_lds_dwordx4 v178, s[14:15]
	s_add_i32 m0, s18, 0x2000
	s_nop 0
	global_load_lds_dwordx4 v144, s[14:15]
	s_waitcnt vmcnt(6)
	s_barrier
	s_setprio 1
	v_mfma_f32_16x16x32_bf16 v[48:51], v[192:195], v[156:159], v[48:51]
	v_mfma_f32_16x16x32_bf16 v[56:59], v[196:199], v[160:163], v[48:51]
	v_mfma_f32_16x16x32_bf16 v[48:51], v[204:207], v[156:159], v[52:55]
	v_mfma_f32_16x16x32_bf16 v[36:39], v[192:195], v[164:167], v[36:39]
	v_mfma_f32_16x16x32_bf16 v[32:35], v[204:207], v[164:167], v[32:35]
	v_mfma_f32_16x16x32_bf16 v[20:23], v[192:195], v[172:175], v[20:23]
	v_mfma_f32_16x16x32_bf16 v[16:19], v[204:207], v[172:175], v[16:19]
	v_mfma_f32_16x16x32_bf16 v[4:7], v[192:195], v[184:187], v[4:7]
	v_mfma_f32_16x16x32_bf16 v[0:3], v[204:207], v[184:187], v[0:3]
	v_mfma_f32_16x16x32_bf16 v[52:55], v[212:215], v[160:163], v[48:51]
	v_mfma_f32_16x16x32_bf16 v[36:39], v[196:199], v[168:171], v[36:39]
	v_mfma_f32_16x16x32_bf16 v[32:35], v[212:215], v[168:171], v[32:35]
	v_mfma_f32_16x16x32_bf16 v[20:23], v[196:199], v[180:183], v[20:23]
	v_mfma_f32_16x16x32_bf16 v[16:19], v[212:215], v[180:183], v[16:19]
	v_mfma_f32_16x16x32_bf16 v[4:7], v[196:199], v[188:191], v[4:7]
	v_mfma_f32_16x16x32_bf16 v[0:3], v[212:215], v[188:191], v[0:3]
	s_setprio 0
	s_add_i32 s67, s67, 2
	s_add_u32 s63, s63, 0x100
	s_addc_u32 s66, s66, 0
	s_cmpk_gt_u32 s67, 0x53
	s_mov_b64 s[14:15], s[16:17]
	s_barrier
	s_cbranch_scc0 .LBB0_1363
	s_lshl_b32 s12, s61, 8
	s_add_i32 s10, s12, 0xfffff000
	s_ashr_i32 s10, s10, 11
	s_add_i32 s10, s10, 1
	s_cmp_gt_i32 s61, 15
	s_cselect_b32 s10, s10, 0
	v_add_u32_e32 v162, s12, v152
	v_lshl_or_b32 v48, s62, 8, v154
	s_mul_hi_i32 s11, s10, 0xc000
	s_mul_i32 s10, s10, 0xc000
	v_ashrrev_i32_e32 v163, 31, v162
	v_readlane_b32 s68, v252, 37
	s_add_u32 s10, s35, s10
	v_ashrrev_i32_e32 v49, 31, v48
	v_lshlrev_b64 v[150:151], 13, v[162:163]
	v_readlane_b32 s82, v252, 51
	v_readlane_b32 s83, v252, 52
	s_addc_u32 s11, s39, s11
	v_lshlrev_b64 v[160:161], 2, v[48:49]
	v_lshl_add_u64 v[150:151], s[82:83], 0, v[150:151]
	v_lshl_add_u64 v[48:49], s[10:11], 0, v[160:161]
	v_lshl_add_u64 v[150:151], v[150:151], 0, v[160:161]
	global_load_dwordx4 v[76:79], v[48:49], off
	global_load_dwordx4 v[72:75], v[48:49], off offset:64
	global_load_dwordx4 v[68:71], v[48:49], off offset:512
	s_nop 0
	global_load_dwordx4 v[48:51], v[48:49], off offset:576
	s_mov_b64 s[10:11], 0x100000
	global_load_dwordx4 v[156:159], v[150:151], off
	s_mov_b32 s62, s59
	s_mov_b32 s61, s60
	s_mov_b64 s[16:17], s[6:7]
	s_mov_b64 s[14:15], s[8:9]
	v_readlane_b32 s69, v252, 38
	v_readlane_b32 s70, v252, 39
	v_readlane_b32 s71, v252, 40
	v_readlane_b32 s72, v252, 41
	v_readlane_b32 s73, v252, 42
	v_readlane_b32 s74, v252, 43
	v_readlane_b32 s75, v252, 44
	v_readlane_b32 s76, v252, 45
	v_readlane_b32 s77, v252, 46
	v_readlane_b32 s78, v252, 47
	v_readlane_b32 s79, v252, 48
	v_readlane_b32 s80, v252, 49
	v_readlane_b32 s81, v252, 50
	s_waitcnt vmcnt(0)
	v_pk_fma_f32 v[142:143], v[142:143], v[78:79], v[158:159]
	v_pk_fma_f32 v[140:141], v[140:141], v[76:77], v[156:157]
	global_store_dwordx4 v[150:151], v[140:143], off
	global_load_dwordx4 v[140:143], v[150:151], off offset:64
	s_waitcnt vmcnt(0)
	v_pk_fma_f32 v[138:139], v[138:139], v[74:75], v[142:143]
	v_pk_fma_f32 v[136:137], v[136:137], v[72:73], v[140:141]
	global_store_dwordx4 v[150:151], v[136:139], off offset:64
	global_load_dwordx4 v[136:139], v[150:151], off offset:512
	s_waitcnt vmcnt(0)
	v_pk_fma_f32 v[134:135], v[134:135], v[70:71], v[138:139]
	v_pk_fma_f32 v[132:133], v[132:133], v[68:69], v[136:137]
	global_store_dwordx4 v[150:151], v[132:135], off offset:512
	global_load_dwordx4 v[132:135], v[150:151], off offset:576
	s_waitcnt vmcnt(0)
	v_pk_fma_f32 v[130:131], v[130:131], v[50:51], v[134:135]
	v_pk_fma_f32 v[128:129], v[128:129], v[48:49], v[132:133]
	global_store_dwordx4 v[150:151], v[128:131], off offset:576
	s_nop 1
	v_or_b32_e32 v128, 16, v162
	v_ashrrev_i32_e32 v129, 31, v128
	v_lshlrev_b64 v[128:129], 13, v[128:129]
	v_lshl_add_u64 v[128:129], s[82:83], 0, v[128:129]
	v_lshl_add_u64 v[132:133], v[128:129], 0, v[160:161]
	global_load_dwordx4 v[128:131], v[132:133], off
	s_waitcnt vmcnt(0)
	v_pk_fma_f32 v[126:127], v[126:127], v[78:79], v[130:131]
	v_pk_fma_f32 v[124:125], v[124:125], v[76:77], v[128:129]
	global_store_dwordx4 v[132:133], v[124:127], off
	global_load_dwordx4 v[124:127], v[132:133], off offset:64
	s_waitcnt vmcnt(0)
	v_pk_fma_f32 v[122:123], v[122:123], v[74:75], v[126:127]
	v_pk_fma_f32 v[120:121], v[120:121], v[72:73], v[124:125]
	global_store_dwordx4 v[132:133], v[120:123], off offset:64
	global_load_dwordx4 v[120:123], v[132:133], off offset:512
	s_waitcnt vmcnt(0)
	v_pk_fma_f32 v[110:111], v[110:111], v[70:71], v[122:123]
	v_pk_fma_f32 v[108:109], v[108:109], v[68:69], v[120:121]
	global_store_dwordx4 v[132:133], v[108:111], off offset:512
	global_load_dwordx4 v[108:111], v[132:133], off offset:576
	s_waitcnt vmcnt(0)
	v_pk_fma_f32 v[106:107], v[106:107], v[50:51], v[110:111]
	v_pk_fma_f32 v[104:105], v[104:105], v[48:49], v[108:109]
	global_store_dwordx4 v[132:133], v[104:107], off offset:576
	s_nop 1
	v_or_b32_e32 v104, 32, v162
	v_ashrrev_i32_e32 v105, 31, v104
	v_lshlrev_b64 v[104:105], 13, v[104:105]
	v_lshl_add_u64 v[104:105], s[82:83], 0, v[104:105]
	v_lshl_add_u64 v[108:109], v[104:105], 0, v[160:161]
	global_load_dwordx4 v[104:107], v[108:109], off
	s_waitcnt vmcnt(0)
	v_pk_fma_f32 v[106:107], v[118:119], v[78:79], v[106:107]
	v_pk_fma_f32 v[104:105], v[116:117], v[76:77], v[104:105]
	global_store_dwordx4 v[108:109], v[104:107], off
	global_load_dwordx4 v[104:107], v[108:109], off offset:64
	s_waitcnt vmcnt(0)
	v_pk_fma_f32 v[106:107], v[114:115], v[74:75], v[106:107]
	v_pk_fma_f32 v[104:105], v[112:113], v[72:73], v[104:105]
	global_store_dwordx4 v[108:109], v[104:107], off offset:64
	global_load_dwordx4 v[104:107], v[108:109], off offset:512
	s_waitcnt vmcnt(0)
	v_pk_fma_f32 v[94:95], v[94:95], v[70:71], v[106:107]
	v_pk_fma_f32 v[92:93], v[92:93], v[68:69], v[104:105]
	global_store_dwordx4 v[108:109], v[92:95], off offset:512
	global_load_dwordx4 v[92:95], v[108:109], off offset:576
	s_waitcnt vmcnt(0)
	v_pk_fma_f32 v[90:91], v[90:91], v[50:51], v[94:95]
	v_pk_fma_f32 v[88:89], v[88:89], v[48:49], v[92:93]
	global_store_dwordx4 v[108:109], v[88:91], off offset:576
	s_nop 1
	v_or_b32_e32 v88, 48, v162
	v_ashrrev_i32_e32 v89, 31, v88
	v_lshlrev_b64 v[88:89], 13, v[88:89]
	v_lshl_add_u64 v[88:89], s[82:83], 0, v[88:89]
	v_lshl_add_u64 v[92:93], v[88:89], 0, v[160:161]
	global_load_dwordx4 v[88:91], v[92:93], off
	s_waitcnt vmcnt(0)
	v_pk_fma_f32 v[90:91], v[102:103], v[78:79], v[90:91]
	v_pk_fma_f32 v[88:89], v[100:101], v[76:77], v[88:89]
	global_store_dwordx4 v[92:93], v[88:91], off
	global_load_dwordx4 v[88:91], v[92:93], off offset:64
	s_waitcnt vmcnt(0)
	v_pk_fma_f32 v[90:91], v[98:99], v[74:75], v[90:91]
	v_pk_fma_f32 v[88:89], v[96:97], v[72:73], v[88:89]
	global_store_dwordx4 v[92:93], v[88:91], off offset:64
	global_load_dwordx4 v[88:91], v[92:93], off offset:512
	s_waitcnt vmcnt(0)
	v_pk_fma_f32 v[86:87], v[86:87], v[70:71], v[90:91]
	v_pk_fma_f32 v[84:85], v[84:85], v[68:69], v[88:89]
	global_store_dwordx4 v[92:93], v[84:87], off offset:512
	global_load_dwordx4 v[84:87], v[92:93], off offset:576
	s_waitcnt vmcnt(0)
	v_pk_fma_f32 v[82:83], v[82:83], v[50:51], v[86:87]
	v_pk_fma_f32 v[80:81], v[80:81], v[48:49], v[84:85]
	global_store_dwordx4 v[92:93], v[80:83], off offset:576
	s_nop 1
	v_lshl_add_u64 v[80:81], v[150:151], 0, s[10:11]
	s_mov_b32 s10, 0x100000
	v_add_co_u32_e32 v86, vcc, s10, v150
	s_mov_b64 s[10:11], 0x120000
	s_nop 0
	v_addc_co_u32_e32 v87, vcc, 0, v151, vcc
	global_load_dwordx4 v[82:85], v[86:87], off
	s_waitcnt vmcnt(0)
	v_pk_fma_f32 v[66:67], v[66:67], v[78:79], v[84:85]
	v_pk_fma_f32 v[64:65], v[64:65], v[76:77], v[82:83]
	global_store_dwordx4 v[86:87], v[64:67], off
	global_load_dwordx4 v[64:67], v[80:81], off offset:64
	s_waitcnt vmcnt(0)
	v_pk_fma_f32 v[62:63], v[62:63], v[74:75], v[66:67]
	v_pk_fma_f32 v[60:61], v[60:61], v[72:73], v[64:65]
	global_store_dwordx4 v[80:81], v[60:63], off offset:64
	global_load_dwordx4 v[60:63], v[80:81], off offset:512
	s_waitcnt vmcnt(0)
	v_pk_fma_f32 v[58:59], v[58:59], v[70:71], v[62:63]
	v_pk_fma_f32 v[56:57], v[56:57], v[68:69], v[60:61]
	global_store_dwordx4 v[80:81], v[56:59], off offset:512
	global_load_dwordx4 v[56:59], v[80:81], off offset:576
	s_waitcnt vmcnt(0)
	v_pk_fma_f32 v[52:53], v[52:53], v[48:49], v[56:57]
	v_lshl_add_u64 v[56:57], v[150:151], 0, s[10:11]
	s_mov_b32 s10, 0x120000
	v_pk_fma_f32 v[54:55], v[54:55], v[50:51], v[58:59]
	v_add_co_u32_e32 v58, vcc, s10, v150
	global_store_dwordx4 v[80:81], v[52:55], off offset:576
	s_nop 0
	v_addc_co_u32_e32 v59, vcc, 0, v151, vcc
	global_load_dwordx4 v[52:55], v[58:59], off
	s_mov_b64 s[10:11], 0x140000
	s_waitcnt vmcnt(0)
	v_pk_fma_f32 v[46:47], v[46:47], v[78:79], v[54:55]
	v_pk_fma_f32 v[44:45], v[44:45], v[76:77], v[52:53]
	global_store_dwordx4 v[58:59], v[44:47], off
	global_load_dwordx4 v[44:47], v[56:57], off offset:64
	s_waitcnt vmcnt(0)
	v_pk_fma_f32 v[42:43], v[42:43], v[74:75], v[46:47]
	v_pk_fma_f32 v[40:41], v[40:41], v[72:73], v[44:45]
	global_store_dwordx4 v[56:57], v[40:43], off offset:64
	global_load_dwordx4 v[40:43], v[56:57], off offset:512
	s_waitcnt vmcnt(0)
	v_pk_fma_f32 v[38:39], v[38:39], v[70:71], v[42:43]
	v_pk_fma_f32 v[36:37], v[36:37], v[68:69], v[40:41]
	global_store_dwordx4 v[56:57], v[36:39], off offset:512
	global_load_dwordx4 v[36:39], v[56:57], off offset:576
	s_waitcnt vmcnt(0)
	v_pk_fma_f32 v[34:35], v[34:35], v[50:51], v[38:39]
	v_pk_fma_f32 v[32:33], v[32:33], v[48:49], v[36:37]
	global_store_dwordx4 v[56:57], v[32:35], off offset:576
	s_nop 1
	v_lshl_add_u64 v[32:33], v[150:151], 0, s[10:11]
	s_mov_b32 s10, 0x140000
	v_add_co_u32_e32 v38, vcc, s10, v150
	s_mov_b64 s[10:11], 0x160000
	s_nop 0
	v_addc_co_u32_e32 v39, vcc, 0, v151, vcc
	global_load_dwordx4 v[34:37], v[38:39], off
	s_waitcnt vmcnt(0)
	v_pk_fma_f32 v[30:31], v[30:31], v[78:79], v[36:37]
	v_pk_fma_f32 v[28:29], v[28:29], v[76:77], v[34:35]
	global_store_dwordx4 v[38:39], v[28:31], off
	global_load_dwordx4 v[28:31], v[32:33], off offset:64
	s_waitcnt vmcnt(0)
	v_pk_fma_f32 v[26:27], v[26:27], v[74:75], v[30:31]
	v_pk_fma_f32 v[24:25], v[24:25], v[72:73], v[28:29]
	global_store_dwordx4 v[32:33], v[24:27], off offset:64
	global_load_dwordx4 v[24:27], v[32:33], off offset:512
	s_waitcnt vmcnt(0)
	v_pk_fma_f32 v[22:23], v[22:23], v[70:71], v[26:27]
	v_pk_fma_f32 v[20:21], v[20:21], v[68:69], v[24:25]
	global_store_dwordx4 v[32:33], v[20:23], off offset:512
	global_load_dwordx4 v[20:23], v[32:33], off offset:576
	s_waitcnt vmcnt(0)
	v_pk_fma_f32 v[18:19], v[18:19], v[50:51], v[22:23]
	v_pk_fma_f32 v[16:17], v[16:17], v[48:49], v[20:21]
	global_store_dwordx4 v[32:33], v[16:19], off offset:576
	s_nop 1
	v_lshl_add_u64 v[16:17], v[150:151], 0, s[10:11]
	s_mov_b32 s10, 0x160000
	v_add_co_u32_e32 v22, vcc, s10, v150
	s_nop 1
	v_addc_co_u32_e32 v23, vcc, 0, v151, vcc
	global_load_dwordx4 v[18:21], v[22:23], off
	s_and_b64 vcc, exec, s[4:5]
	s_waitcnt vmcnt(0)
	v_pk_fma_f32 v[14:15], v[14:15], v[78:79], v[20:21]
	v_pk_fma_f32 v[12:13], v[12:13], v[76:77], v[18:19]
	global_store_dwordx4 v[22:23], v[12:15], off
	global_load_dwordx4 v[12:15], v[16:17], off offset:64
	s_waitcnt vmcnt(0)
	v_pk_fma_f32 v[10:11], v[10:11], v[74:75], v[14:15]
	v_pk_fma_f32 v[8:9], v[8:9], v[72:73], v[12:13]
	global_store_dwordx4 v[16:17], v[8:11], off offset:64
	global_load_dwordx4 v[8:11], v[16:17], off offset:512
	s_waitcnt vmcnt(0)
	v_pk_fma_f32 v[6:7], v[6:7], v[70:71], v[10:11]
	v_pk_fma_f32 v[4:5], v[4:5], v[68:69], v[8:9]
	global_store_dwordx4 v[16:17], v[4:7], off offset:512
	global_load_dwordx4 v[4:7], v[16:17], off offset:576
	s_waitcnt vmcnt(0)
	v_pk_fma_f32 v[2:3], v[2:3], v[50:51], v[6:7]
	v_pk_fma_f32 v[0:1], v[0:1], v[48:49], v[4:5]
	global_store_dwordx4 v[16:17], v[0:3], off offset:576
	s_cbranch_vccz .LBB0_1360
	s_waitcnt vmcnt(0)
	s_mov_b32 s4, s86
	s_cmp_gt_u32 s4, 3
	s_movk_i32 s57, 0x404
	s_cbranch_scc1 .LBB0_1367
	s_barrier

	.amdhsa_kernel _Z14fwd_megakernel6Params
		.amdhsa_group_segment_fixed_size 0
		.amdhsa_private_segment_fixed_size 0
		.amdhsa_kernarg_size 528
		.amdhsa_user_sgpr_count 2
		.amdhsa_user_sgpr_dispatch_ptr 0
		.amdhsa_user_sgpr_queue_ptr 0
		.amdhsa_user_sgpr_kernarg_segment_ptr 1
		.amdhsa_user_sgpr_dispatch_id 0
		.amdhsa_user_sgpr_kernarg_preload_length 0
		.amdhsa_user_sgpr_kernarg_preload_offset 0
		.amdhsa_user_sgpr_private_segment_size 0
		.amdhsa_uses_dynamic_stack 0
		.amdhsa_enable_private_segment 0
		.amdhsa_system_sgpr_workgroup_id_x 1
		.amdhsa_system_sgpr_workgroup_id_y 0
		.amdhsa_system_sgpr_workgroup_id_z 0
		.amdhsa_system_sgpr_workgroup_info 0
		.amdhsa_system_vgpr_workitem_id 2
		.amdhsa_next_free_vgpr 256
		.amdhsa_next_free_sgpr 102
		.amdhsa_accum_offset 256
		.amdhsa_reserve_vcc 1
		.amdhsa_float_round_mode_32 0
		.amdhsa_float_round_mode_16_64 0
		.amdhsa_float_denorm_mode_32 3
		.amdhsa_float_denorm_mode_16_64 3
		.amdhsa_dx10_clamp 1
		.amdhsa_ieee_mode 1
		.amdhsa_fp16_overflow 0
		.amdhsa_tg_split 0
		.amdhsa_exception_fp_ieee_invalid_op 0
		.amdhsa_exception_fp_denorm_src 0
		.amdhsa_exception_fp_ieee_div_zero 0
		.amdhsa_exception_fp_ieee_overflow 0
		.amdhsa_exception_fp_ieee_underflow 0
		.amdhsa_exception_fp_ieee_inexact 0
		.amdhsa_exception_int_div_zero 0
	.end_amdhsa_kernel

amdhsa.kernels:
  - .agpr_count:     0
    .args:
      - .offset:         0
        .size:           272
        .value_kind:     by_value
      - .offset:         272
        .size:           4
        .value_kind:     hidden_block_count_x
      - .offset:         276
        .size:           4
        .value_kind:     hidden_block_count_y
      - .offset:         280
        .size:           4
        .value_kind:     hidden_block_count_z
      - .offset:         284
        .size:           2
        .value_kind:     hidden_group_size_x
      - .offset:         286
        .size:           2
        .value_kind:     hidden_group_size_y
      - .offset:         288
        .size:           2
        .value_kind:     hidden_group_size_z
      - .offset:         290
        .size:           2
        .value_kind:     hidden_remainder_x
      - .offset:         292
        .size:           2
        .value_kind:     hidden_remainder_y
      - .offset:         294
        .size:           2
        .value_kind:     hidden_remainder_z
      - .offset:         312
        .size:           8
        .value_kind:     hidden_global_offset_x
      - .offset:         320
        .size:           8
        .value_kind:     hidden_global_offset_y
      - .offset:         328
        .size:           8
        .value_kind:     hidden_global_offset_z
      - .offset:         336
        .size:           2
        .value_kind:     hidden_grid_dims
      - .offset:         360
        .size:           8
        .value_kind:     hidden_multigrid_sync_arg
      - .offset:         392
        .size:           4
        .value_kind:     hidden_dynamic_lds_size
    .group_segment_fixed_size: 0
    .kernarg_segment_align: 8
    .kernarg_segment_size: 528
    .language:       OpenCL C
    .language_version:
      - 2
      - 0
    .max_flat_workgroup_size: 512
    .name:           _Z14fwd_megakernel6Params
    .private_segment_fixed_size: 0
    .sgpr_count:     108
    .sgpr_spill_count: 510
    .symbol:         _Z14fwd_megakernel6Params.kd
    .uniform_work_group_size: 1
    .uses_dynamic_stack: false
    .vgpr_count:     256
    .vgpr_spill_count: 0
    .wavefront_size: 64
